# GEMM K-loops: every SALU/s_setprio between a segment's last pre-barrier MFMA and its s_barrier moved behind the barrier (barrier signalled immediately after the MFMA issue); loop counter updates and e
# speedup vs baseline: 1.0210x; 1.0210x over previous
; #define PG8_STAGE(bufoff, gbase, voff) do { _Pragma("unroll") for (int _i = 0; _i < 2; ++_i) \
;         __builtin_amdgcn_global_load_lds((const unsigned*)((const char*)(gbase) + (voff)[_i]), (LAS unsigned*)(lds + (bufoff) + ldsw + _i * 8192), 16, 0, 0); } while (0)
; #define PG8_LDA(dst, b, h) do { _Pragma("unroll") for (int m = 0; m < 4; ++m) _Pragma("unroll") for (int k = 0; k < 2; ++k) dst[m][k] = *(const LAS bf16x8*)(lds + PG8_SA(b, h) + aoff + m * 2048 + k * 1024); } while (0)
; #define PG8_LDB(dst, b, h) do { _Pragma("unroll") for (int n = 0; n < 2; ++n) _Pragma("unroll") for (int k = 0; k < 2; ++k) dst[n][k] = *(const LAS bf16x8*)(lds + PG8_SB(b, h) + boff + n * 2048 + k * 1024); } while (0)
; #define PG8_WAIT_V(n) asm volatile("s_waitcnt vmcnt(" #n ")" ::: "memory")
; template <class Epi, class Sched, int LD>
; __device__ __forceinline__ void gemm_phase(LAS unsigned char* lds, const Gemm g, const Sched& S, const Epi& E) {
;     ...
;     for (;;) {
;         const bool has_next = S.next(ui + 1, nxt);
;         const char* nA = has_next ? (const char*)g.A + (size_t)nxt.pm * tstep + (size_t)(nxt.kofs / BK) * kstep : cA; const char* nB = has_next ? (const char*)g.Bt + (size_t)nxt.pn * tstep + (size_t)(nxt.kofs / BK) * kstep : cB;
;         const int nt = cur.nt;
;         for (int t = 0; t < nt; t += 2) {
;             const bool last = (t == nt - 2);
;             const char* a1 = cA + (size_t)(t + 1) * kstep;
;             const char* a2 = last ? nA : cA + (size_t)(t + 2) * kstep; const char* b2 = last ? nB : cB + (size_t)(t + 2) * kstep;
;             const char* a3 = a2 + kstep; const char* b3 = b2 + kstep;
;             PG8_LDB(B0, 0, 0); PG8_SCHED; PG8_LDA(At, 0, 0); PG8_STAGE(PG8_SA(1, 1), a1 + hstep, voffA);
;             PG8_WAIT_L(8); PG8_BAR; PG8_WAIT_L(0); PG8_MMA(0, 0, At, B0); PG8_BAR; PG8_SCHED;
;             PG8_LDB(B1, 0, 1); PG8_STAGE(PG8_SB(0, 0), b2, voffB);
;             PG8_BAR; PG8_WAIT_L(0); PG8_MMA(0, 1, At, B1); PG8_BAR;
;             PG8_LDA(At, 0, 1); PG8_STAGE(PG8_SA(0, 0), a2, voffA);
;             PG8_BAR; PG8_WAIT_L(0); PG8_MMA(1, 0, At, B0); PG8_BAR; PG8_SCHED;
;             PG8_STAGE(PG8_SB(0, 1), b2 + hstep, voffB);
;             PG8_WAIT_V(6); PG8_BAR; PG8_MMA(1, 1, At, B1); PG8_BAR;
;             PG8_LDB(B0, 1, 0); PG8_SCHED; PG8_LDA(At, 1, 0); PG8_STAGE(PG8_SA(0, 1), a2 + hstep, voffA);
.LBB0_58:
	s_add_i32 s71, s4, 2
	s_add_u32 s48, s46, 0x4000
	s_addc_u32 s5, s47, 0
	s_cmp_eq_u32 s68, s4
	s_cselect_b32 s4, s42, s48
	s_cselect_b32 s5, s43, s5
	s_cselect_b32 s48, s44, s69
	s_cselect_b32 s49, s45, s70
	s_add_u32 s50, s4, 0x8000
	s_addc_u32 s51, s5, 0
	s_add_i32 s72, 0, 0x10000
	s_add_i32 m0, s39, 0xc000
	ds_read_b128 v[180:183], v148
	ds_read_b128 v[184:187], v148 offset:1024
	ds_read_b128 v[188:191], v148 offset:2048
	ds_read_b128 v[192:195], v148 offset:3072
	ds_read_b128 v[196:199], v148 offset:4096
	ds_read_b128 v[200:203], v148 offset:5120
	ds_read_b128 v[204:207], v148 offset:6144
	ds_read_b128 v[208:211], v148 offset:7168
	global_load_lds_dwordx4 v132, s[46:47]
	s_add_i32 m0, s39, 0xe000
	s_nop 0
	global_load_lds_dwordx4 v138, s[46:47]
	s_waitcnt lgkmcnt(8)
	s_barrier
	s_waitcnt lgkmcnt(0)
	s_setprio 0
	v_mfma_f32_16x16x32_bf16 v[128:131], v[140:143], v[180:183], v[128:131]
	v_mfma_f32_16x16x32_bf16 v[124:127], v[154:157], v[180:183], v[124:127]
	v_mfma_f32_16x16x32_bf16 v[112:115], v[140:143], v[188:191], v[112:115]
	v_mfma_f32_16x16x32_bf16 v[108:111], v[154:157], v[188:191], v[108:111]
	v_mfma_f32_16x16x32_bf16 v[96:99], v[140:143], v[196:199], v[96:99]
	v_mfma_f32_16x16x32_bf16 v[92:95], v[154:157], v[196:199], v[92:95]
	v_mfma_f32_16x16x32_bf16 v[80:83], v[140:143], v[204:207], v[80:83]
	v_mfma_f32_16x16x32_bf16 v[76:79], v[154:157], v[204:207], v[76:79]
	v_mfma_f32_16x16x32_bf16 v[128:131], v[150:153], v[184:187], v[128:131]
	v_mfma_f32_16x16x32_bf16 v[124:127], v[176:179], v[184:187], v[124:127]
	v_mfma_f32_16x16x32_bf16 v[112:115], v[150:153], v[192:195], v[112:115]
	v_mfma_f32_16x16x32_bf16 v[108:111], v[176:179], v[192:195], v[108:111]
	v_mfma_f32_16x16x32_bf16 v[96:99], v[150:153], v[200:203], v[96:99]
	v_mfma_f32_16x16x32_bf16 v[92:95], v[176:179], v[200:203], v[92:95]
	s_barrier
	s_setprio 3
	v_mfma_f32_16x16x32_bf16 v[80:83], v[150:153], v[208:211], v[80:83]
	v_mfma_f32_16x16x32_bf16 v[76:79], v[176:179], v[208:211], v[76:79]
	s_setprio 2
	s_add_i32 s74, 0, 0x14000
	s_add_i32 s72, s72, s29
	ds_read_b128 v[212:215], v228 offset:16384
	ds_read_b128 v[216:219], v228 offset:17408
	ds_read_b128 v[220:223], v228 offset:18432
	ds_read_b128 v[224:227], v228 offset:19456
	s_mov_b32 m0, s72
	s_nop 0
	global_load_lds_dwordx4 v132, s[48:49]
	s_add_i32 m0, s72, 0x2000
	s_nop 0
	global_load_lds_dwordx4 v138, s[48:49]
	s_barrier
	s_waitcnt lgkmcnt(0)
	s_setprio 0
	v_mfma_f32_16x16x32_bf16 v[120:123], v[212:215], v[180:183], v[120:123]
	v_mfma_f32_16x16x32_bf16 v[116:119], v[220:223], v[180:183], v[116:119]
	v_mfma_f32_16x16x32_bf16 v[104:107], v[212:215], v[188:191], v[104:107]
	v_mfma_f32_16x16x32_bf16 v[100:103], v[220:223], v[188:191], v[100:103]
	v_mfma_f32_16x16x32_bf16 v[88:91], v[212:215], v[196:199], v[88:91]
	v_mfma_f32_16x16x32_bf16 v[84:87], v[220:223], v[196:199], v[84:87]
	v_mfma_f32_16x16x32_bf16 v[72:75], v[212:215], v[204:207], v[72:75]
	v_mfma_f32_16x16x32_bf16 v[68:71], v[220:223], v[204:207], v[68:71]
	v_mfma_f32_16x16x32_bf16 v[120:123], v[216:219], v[184:187], v[120:123]
	v_mfma_f32_16x16x32_bf16 v[116:119], v[224:227], v[184:187], v[116:119]
	v_mfma_f32_16x16x32_bf16 v[104:107], v[216:219], v[192:195], v[104:107]
	v_mfma_f32_16x16x32_bf16 v[100:103], v[224:227], v[192:195], v[100:103]
	v_mfma_f32_16x16x32_bf16 v[88:91], v[216:219], v[200:203], v[88:91]
	v_mfma_f32_16x16x32_bf16 v[84:87], v[224:227], v[200:203], v[84:87]
	v_mfma_f32_16x16x32_bf16 v[72:75], v[216:219], v[208:211], v[72:75]
	v_mfma_f32_16x16x32_bf16 v[68:71], v[224:227], v[208:211], v[68:71]
	s_barrier
	s_setprio 2
	s_mov_b32 m0, s39
	ds_read_b128 v[180:183], v148 offset:16384
	ds_read_b128 v[184:187], v148 offset:17408
	ds_read_b128 v[188:191], v148 offset:18432
	ds_read_b128 v[192:195], v148 offset:19456
	ds_read_b128 v[196:199], v148 offset:20480
	ds_read_b128 v[200:203], v148 offset:21504
	ds_read_b128 v[204:207], v148 offset:22528
	ds_read_b128 v[208:211], v148 offset:23552
	global_load_lds_dwordx4 v132, s[4:5]
	s_mov_b32 m0, s52
	s_nop 0
	global_load_lds_dwordx4 v138, s[4:5]
	s_waitcnt vmcnt(10)
	s_barrier
	s_waitcnt lgkmcnt(0)
	s_setprio 0
	v_mfma_f32_16x16x32_bf16 v[64:67], v[140:143], v[180:183], v[64:67]
	v_mfma_f32_16x16x32_bf16 v[60:63], v[154:157], v[180:183], v[60:63]
	v_mfma_f32_16x16x32_bf16 v[48:51], v[140:143], v[188:191], v[48:51]
	v_mfma_f32_16x16x32_bf16 v[44:47], v[154:157], v[188:191], v[44:47]
	v_mfma_f32_16x16x32_bf16 v[32:35], v[140:143], v[196:199], v[32:35]
	v_mfma_f32_16x16x32_bf16 v[28:31], v[154:157], v[196:199], v[28:31]
	v_mfma_f32_16x16x32_bf16 v[16:19], v[140:143], v[204:207], v[16:19]
	v_mfma_f32_16x16x32_bf16 v[12:15], v[154:157], v[204:207], v[12:15]
	v_mfma_f32_16x16x32_bf16 v[64:67], v[150:153], v[184:187], v[64:67]
	v_mfma_f32_16x16x32_bf16 v[60:63], v[176:179], v[184:187], v[60:63]
	v_mfma_f32_16x16x32_bf16 v[48:51], v[150:153], v[192:195], v[48:51]
	v_mfma_f32_16x16x32_bf16 v[44:47], v[176:179], v[192:195], v[44:47]
	v_mfma_f32_16x16x32_bf16 v[32:35], v[150:153], v[200:203], v[32:35]
	v_mfma_f32_16x16x32_bf16 v[28:31], v[176:179], v[200:203], v[28:31]
	s_barrier
	s_setprio 3
	v_mfma_f32_16x16x32_bf16 v[16:19], v[150:153], v[208:211], v[16:19]
	v_mfma_f32_16x16x32_bf16 v[12:15], v[176:179], v[208:211], v[12:15]
	s_setprio 2
	ds_read_b128 v[140:143], v228 offset:32768
	ds_read_b128 v[150:153], v228 offset:33792
	ds_read_b128 v[154:157], v228 offset:34816
	ds_read_b128 v[176:179], v228 offset:35840
	s_add_u32 s72, s48, 0x4000
	s_addc_u32 s73, s49, 0
	s_add_i32 s74, s74, s29
	s_mov_b32 m0, s74
	s_nop 0
	global_load_lds_dwordx4 v132, s[72:73]
	s_add_i32 m0, s74, 0x2000
	s_nop 0
	global_load_lds_dwordx4 v138, s[72:73]
	s_waitcnt vmcnt(6)
	s_barrier
; #define PG8_STAGE(bufoff, gbase, voff) do { _Pragma("unroll") for (int _i = 0; _i < 2; ++_i) \
;         __builtin_amdgcn_global_load_lds((const unsigned*)((const char*)(gbase) + (voff)[_i]), (LAS unsigned*)(lds + (bufoff) + ldsw + _i * 8192), 16, 0, 0); } while (0)
; #define PG8_LDA(dst, b, h) do { _Pragma("unroll") for (int m = 0; m < 4; ++m) _Pragma("unroll") for (int k = 0; k < 2; ++k) dst[m][k] = *(const LAS bf16x8*)(lds + PG8_SA(b, h) + aoff + m * 2048 + k * 1024); } while (0)
; #define PG8_LDB(dst, b, h) do { _Pragma("unroll") for (int n = 0; n < 2; ++n) _Pragma("unroll") for (int k = 0; k < 2; ++k) dst[n][k] = *(const LAS bf16x8*)(lds + PG8_SB(b, h) + boff + n * 2048 + k * 1024); } while (0)
; #define PG8_MMA(ai, bj, At, Bt) do { __builtin_amdgcn_s_setprio(1); _Pragma("unroll") for (int m = 0; m < 4; ++m) _Pragma("unroll") for (int n = 0; n < 2; ++n) _Pragma("unroll") for (int k = 0; k < 2; ++k) \
;         acc[ai][bj][m][n] = __builtin_amdgcn_mfma_f32_16x16x32_bf16(Bt[n][k], At[m][k], acc[ai][bj][m][n], 0, 0, 0); __builtin_amdgcn_s_setprio(0); } while (0)
; #define PG8_WAIT_V(n) asm volatile("s_waitcnt vmcnt(" #n ")" ::: "memory")
; #define PG8_WAIT_L(n) asm volatile("s_waitcnt lgkmcnt(" #n ")" ::: "memory")
; #define PG8_BAR __builtin_amdgcn_s_barrier()
; #define PG8_SCHED __builtin_amdgcn_sched_barrier(0)
; template <class Epi, class Sched, int LD>
; __device__ __forceinline__ void gemm_phase(LAS unsigned char* lds, const Gemm g, const Sched& S, const Epi& E) {
;     ...
;             PG8_WAIT_V(6); PG8_BAR; PG8_MMA(1, 1, At, B1); PG8_BAR;
;             PG8_LDB(B0, 1, 0); PG8_SCHED; PG8_LDA(At, 1, 0); PG8_STAGE(PG8_SA(0, 1), a2 + hstep, voffA);
;             PG8_WAIT_L(8); PG8_BAR; PG8_WAIT_L(0); PG8_MMA(0, 0, At, B0); PG8_BAR; PG8_SCHED;
;             PG8_LDB(B1, 1, 1); PG8_STAGE(PG8_SB(1, 0), b3, voffB);
;             PG8_BAR; PG8_WAIT_L(0); PG8_MMA(0, 1, At, B1); PG8_BAR;
;             PG8_LDA(At, 1, 1); PG8_STAGE(PG8_SA(1, 0), a3, voffA);
;             PG8_BAR; PG8_WAIT_L(0); PG8_MMA(1, 0, At, B0); PG8_BAR; PG8_SCHED;
	s_setprio 0
	v_mfma_f32_16x16x32_bf16 v[56:59], v[212:215], v[180:183], v[56:59]
	v_mfma_f32_16x16x32_bf16 v[52:55], v[220:223], v[180:183], v[52:55]
	v_mfma_f32_16x16x32_bf16 v[40:43], v[212:215], v[188:191], v[40:43]
	v_mfma_f32_16x16x32_bf16 v[36:39], v[220:223], v[188:191], v[36:39]
	v_mfma_f32_16x16x32_bf16 v[24:27], v[212:215], v[196:199], v[24:27]
	v_mfma_f32_16x16x32_bf16 v[20:23], v[220:223], v[196:199], v[20:23]
	v_mfma_f32_16x16x32_bf16 v[8:11], v[212:215], v[204:207], v[8:11]
	v_mfma_f32_16x16x32_bf16 v[4:7], v[220:223], v[204:207], v[4:7]
	v_mfma_f32_16x16x32_bf16 v[56:59], v[216:219], v[184:187], v[56:59]
	v_mfma_f32_16x16x32_bf16 v[52:55], v[224:227], v[184:187], v[52:55]
	v_mfma_f32_16x16x32_bf16 v[40:43], v[216:219], v[192:195], v[40:43]
	v_mfma_f32_16x16x32_bf16 v[36:39], v[224:227], v[192:195], v[36:39]
	v_mfma_f32_16x16x32_bf16 v[24:27], v[216:219], v[200:203], v[24:27]
	v_mfma_f32_16x16x32_bf16 v[20:23], v[224:227], v[200:203], v[20:23]
	v_mfma_f32_16x16x32_bf16 v[8:11], v[216:219], v[208:211], v[8:11]
	v_mfma_f32_16x16x32_bf16 v[4:7], v[224:227], v[208:211], v[4:7]
	s_barrier
	s_setprio 2
	s_add_i32 s72, 0, 0x18000
	s_add_u32 s4, s4, 0x4000
	s_addc_u32 s5, s5, 0
	s_mov_b32 m0, s53
	ds_read_b128 v[180:183], v148 offset:32768
	ds_read_b128 v[184:187], v148 offset:33792
	ds_read_b128 v[188:191], v148 offset:34816
	ds_read_b128 v[192:195], v148 offset:35840
	ds_read_b128 v[196:199], v148 offset:36864
	ds_read_b128 v[200:203], v148 offset:37888
	ds_read_b128 v[204:207], v148 offset:38912
	ds_read_b128 v[208:211], v148 offset:39936
	global_load_lds_dwordx4 v132, s[4:5]
	s_mov_b32 m0, s54
	s_nop 0
	global_load_lds_dwordx4 v138, s[4:5]
	s_waitcnt lgkmcnt(8)
	s_barrier
	s_waitcnt lgkmcnt(0)
	s_setprio 0
	v_mfma_f32_16x16x32_bf16 v[128:131], v[140:143], v[180:183], v[128:131]
	v_mfma_f32_16x16x32_bf16 v[124:127], v[154:157], v[180:183], v[124:127]
	v_mfma_f32_16x16x32_bf16 v[112:115], v[140:143], v[188:191], v[112:115]
	v_mfma_f32_16x16x32_bf16 v[108:111], v[154:157], v[188:191], v[108:111]
	v_mfma_f32_16x16x32_bf16 v[96:99], v[140:143], v[196:199], v[96:99]
	v_mfma_f32_16x16x32_bf16 v[92:95], v[154:157], v[196:199], v[92:95]
	v_mfma_f32_16x16x32_bf16 v[80:83], v[140:143], v[204:207], v[80:83]
	v_mfma_f32_16x16x32_bf16 v[76:79], v[154:157], v[204:207], v[76:79]
	v_mfma_f32_16x16x32_bf16 v[128:131], v[150:153], v[184:187], v[128:131]
	v_mfma_f32_16x16x32_bf16 v[124:127], v[176:179], v[184:187], v[124:127]
	v_mfma_f32_16x16x32_bf16 v[112:115], v[150:153], v[192:195], v[112:115]
	v_mfma_f32_16x16x32_bf16 v[108:111], v[176:179], v[192:195], v[108:111]
	v_mfma_f32_16x16x32_bf16 v[96:99], v[150:153], v[200:203], v[96:99]
	v_mfma_f32_16x16x32_bf16 v[92:95], v[176:179], v[200:203], v[92:95]
	s_barrier
	s_setprio 3
	v_mfma_f32_16x16x32_bf16 v[80:83], v[150:153], v[208:211], v[80:83]
	v_mfma_f32_16x16x32_bf16 v[76:79], v[176:179], v[208:211], v[76:79]
	s_setprio 2
	s_add_i32 s73, 0, 0x1c000
	s_add_u32 s4, s48, 0x8000
	s_addc_u32 s5, s49, 0
	s_add_i32 s72, s72, s29
	ds_read_b128 v[212:215], v228 offset:49152
	ds_read_b128 v[216:219], v228 offset:50176
	ds_read_b128 v[220:223], v228 offset:51200
	ds_read_b128 v[224:227], v228 offset:52224
	s_mov_b32 m0, s72
	s_nop 0
	global_load_lds_dwordx4 v132, s[4:5]
	s_add_i32 m0, s72, 0x2000
	s_nop 0
	global_load_lds_dwordx4 v138, s[4:5]
	s_barrier
	s_waitcnt lgkmcnt(0)
	s_setprio 0
	v_mfma_f32_16x16x32_bf16 v[120:123], v[212:215], v[180:183], v[120:123]
	v_mfma_f32_16x16x32_bf16 v[116:119], v[220:223], v[180:183], v[116:119]
	v_mfma_f32_16x16x32_bf16 v[104:107], v[212:215], v[188:191], v[104:107]
	v_mfma_f32_16x16x32_bf16 v[100:103], v[220:223], v[188:191], v[100:103]
	v_mfma_f32_16x16x32_bf16 v[88:91], v[212:215], v[196:199], v[88:91]
	v_mfma_f32_16x16x32_bf16 v[84:87], v[220:223], v[196:199], v[84:87]
	v_mfma_f32_16x16x32_bf16 v[72:75], v[212:215], v[204:207], v[72:75]
	v_mfma_f32_16x16x32_bf16 v[68:71], v[220:223], v[204:207], v[68:71]
	v_mfma_f32_16x16x32_bf16 v[120:123], v[216:219], v[184:187], v[120:123]
	v_mfma_f32_16x16x32_bf16 v[116:119], v[224:227], v[184:187], v[116:119]
	v_mfma_f32_16x16x32_bf16 v[104:107], v[216:219], v[192:195], v[104:107]
	v_mfma_f32_16x16x32_bf16 v[100:103], v[224:227], v[192:195], v[100:103]
	v_mfma_f32_16x16x32_bf16 v[88:91], v[216:219], v[200:203], v[88:91]
	v_mfma_f32_16x16x32_bf16 v[84:87], v[224:227], v[200:203], v[84:87]
	v_mfma_f32_16x16x32_bf16 v[72:75], v[216:219], v[208:211], v[72:75]
	v_mfma_f32_16x16x32_bf16 v[68:71], v[224:227], v[208:211], v[68:71]
	s_barrier
	s_setprio 2
	s_mov_b32 m0, s55
	ds_read_b128 v[180:183], v148 offset:49152
	ds_read_b128 v[184:187], v148 offset:50176
	ds_read_b128 v[188:191], v148 offset:51200
	ds_read_b128 v[192:195], v148 offset:52224
	ds_read_b128 v[196:199], v148 offset:53248
	ds_read_b128 v[200:203], v148 offset:54272
	ds_read_b128 v[204:207], v148 offset:55296
	ds_read_b128 v[208:211], v148 offset:56320
	global_load_lds_dwordx4 v132, s[50:51]
	s_mov_b32 m0, s56
	s_nop 0
	global_load_lds_dwordx4 v138, s[50:51]
	s_waitcnt vmcnt(10)
	s_barrier
	s_waitcnt lgkmcnt(0)
	s_setprio 0
	v_mfma_f32_16x16x32_bf16 v[64:67], v[140:143], v[180:183], v[64:67]
	v_mfma_f32_16x16x32_bf16 v[60:63], v[154:157], v[180:183], v[60:63]
	v_mfma_f32_16x16x32_bf16 v[48:51], v[140:143], v[188:191], v[48:51]
	v_mfma_f32_16x16x32_bf16 v[44:47], v[154:157], v[188:191], v[44:47]
	v_mfma_f32_16x16x32_bf16 v[32:35], v[140:143], v[196:199], v[32:35]
	v_mfma_f32_16x16x32_bf16 v[28:31], v[154:157], v[196:199], v[28:31]
	v_mfma_f32_16x16x32_bf16 v[16:19], v[140:143], v[204:207], v[16:19]
	v_mfma_f32_16x16x32_bf16 v[12:15], v[154:157], v[204:207], v[12:15]
	v_mfma_f32_16x16x32_bf16 v[64:67], v[150:153], v[184:187], v[64:67]
	v_mfma_f32_16x16x32_bf16 v[60:63], v[176:179], v[184:187], v[60:63]
	v_mfma_f32_16x16x32_bf16 v[48:51], v[150:153], v[192:195], v[48:51]
	v_mfma_f32_16x16x32_bf16 v[44:47], v[176:179], v[192:195], v[44:47]
	v_mfma_f32_16x16x32_bf16 v[32:35], v[150:153], v[200:203], v[32:35]
	v_mfma_f32_16x16x32_bf16 v[28:31], v[176:179], v[200:203], v[28:31]
	s_barrier
; #define PG8_STAGE(bufoff, gbase, voff) do { _Pragma("unroll") for (int _i = 0; _i < 2; ++_i) \
;         __builtin_amdgcn_global_load_lds((const unsigned*)((const char*)(gbase) + (voff)[_i]), (LAS unsigned*)(lds + (bufoff) + ldsw + _i * 8192), 16, 0, 0); } while (0)
; #define PG8_MMA(ai, bj, At, Bt) do { __builtin_amdgcn_s_setprio(1); _Pragma("unroll") for (int m = 0; m < 4; ++m) _Pragma("unroll") for (int n = 0; n < 2; ++n) _Pragma("unroll") for (int k = 0; k < 2; ++k) \
;         acc[ai][bj][m][n] = __builtin_amdgcn_mfma_f32_16x16x32_bf16(Bt[n][k], At[m][k], acc[ai][bj][m][n], 0, 0, 0); __builtin_amdgcn_s_setprio(0); } while (0)
; #define PG8_WAIT_V(n) asm volatile("s_waitcnt vmcnt(" #n ")" ::: "memory")
; #define PG8_WAIT_L(n) asm volatile("s_waitcnt lgkmcnt(" #n ")" ::: "memory")
; #define PG8_BAR __builtin_amdgcn_s_barrier()
; #define PG8_SCHED __builtin_amdgcn_sched_barrier(0)
;     __device__ __forceinline__ void operator()(const f32x4 (&acc)[2][2][4][2], const Unit& u, int wr, int wc, int fr, int fq) const {
;     ...
;         } else {
;             float* base = PART + (size_t)u.part * (512 * 2048);
; #pragma unroll
;             for (int ai = 0; ai < 2; ++ai)
; #pragma unroll
;                 for (int m = 0; m < 4; ++m) {
;                     float* rowp = base + (size_t)(row0 - 8192 + ai * HALF + m * 16) * D_MODEL + col0;
; #pragma unroll
;                     for (int bj = 0; bj < 2; ++bj)
; #pragma unroll
;                         for (int n = 0; n < 2; ++n) *(f32x4*)(rowp + bj * HALF + n * 16) = acc[ai][bj][m][n];
;                 }
; template <class Epi, class Sched, int LD>
; __device__ __forceinline__ void gemm_phase(LAS unsigned char* lds, const Gemm g, const Sched& S, const Epi& E) {
;     ...
;             PG8_BAR; PG8_WAIT_L(0); PG8_MMA(1, 0, At, B0); PG8_BAR; PG8_SCHED;
;             PG8_STAGE(PG8_SB(1, 1), b3 + hstep, voffB);
;             PG8_WAIT_V(6); PG8_BAR; PG8_MMA(1, 1, At, B1); PG8_BAR;
;         }
	s_setprio 3
	v_mfma_f32_16x16x32_bf16 v[16:19], v[150:153], v[208:211], v[16:19]
	v_mfma_f32_16x16x32_bf16 v[12:15], v[176:179], v[208:211], v[12:15]
	s_setprio 2
	ds_read_b128 v[140:143], v228
	ds_read_b128 v[150:153], v228 offset:1024
	ds_read_b128 v[154:157], v228 offset:2048
	ds_read_b128 v[176:179], v228 offset:3072
	s_add_u32 s4, s48, 0xc000
	s_addc_u32 s5, s49, 0
	s_add_i32 s48, s73, s29
	s_mov_b32 m0, s48
	s_nop 0
	global_load_lds_dwordx4 v132, s[4:5]
	s_add_i32 m0, s48, 0x2000
	s_nop 0
	global_load_lds_dwordx4 v138, s[4:5]
	s_waitcnt vmcnt(6)
	s_barrier
	s_setprio 0
	v_mfma_f32_16x16x32_bf16 v[56:59], v[212:215], v[180:183], v[56:59]
	v_mfma_f32_16x16x32_bf16 v[52:55], v[220:223], v[180:183], v[52:55]
	v_mfma_f32_16x16x32_bf16 v[40:43], v[212:215], v[188:191], v[40:43]
	v_mfma_f32_16x16x32_bf16 v[36:39], v[220:223], v[188:191], v[36:39]
	v_mfma_f32_16x16x32_bf16 v[24:27], v[212:215], v[196:199], v[24:27]
	v_mfma_f32_16x16x32_bf16 v[20:23], v[220:223], v[196:199], v[20:23]
	v_mfma_f32_16x16x32_bf16 v[8:11], v[212:215], v[204:207], v[8:11]
	v_mfma_f32_16x16x32_bf16 v[4:7], v[220:223], v[204:207], v[4:7]
	v_mfma_f32_16x16x32_bf16 v[56:59], v[216:219], v[184:187], v[56:59]
	v_mfma_f32_16x16x32_bf16 v[52:55], v[224:227], v[184:187], v[52:55]
	v_mfma_f32_16x16x32_bf16 v[40:43], v[216:219], v[192:195], v[40:43]
	v_mfma_f32_16x16x32_bf16 v[36:39], v[224:227], v[192:195], v[36:39]
	v_mfma_f32_16x16x32_bf16 v[24:27], v[216:219], v[200:203], v[24:27]
	v_mfma_f32_16x16x32_bf16 v[20:23], v[224:227], v[200:203], v[20:23]
	v_mfma_f32_16x16x32_bf16 v[8:11], v[216:219], v[208:211], v[8:11]
	v_mfma_f32_16x16x32_bf16 v[4:7], v[224:227], v[208:211], v[4:7]
	s_barrier
	s_setprio 2
	s_add_u32 s46, s46, 0x10000
	s_addc_u32 s47, s47, 0
	s_add_u32 s69, s69, 0x10000
	s_addc_u32 s70, s70, 0
	s_cmp_ge_i32 s71, s65
	s_mov_b32 s4, s71
	s_cbranch_scc0 .LBB0_58
	s_setprio 0
	v_lshl_add_u32 v142, s67, 8, v137
	v_lshl_or_b32 v140, s66, 8, v147
	s_mov_b64 s[4:5], -1
	s_cmp_gt_i32 s18, -1
	v_ashrrev_i32_e32 v141, 31, v140
	v_ashrrev_i32_e32 v143, 31, v142
	s_cbranch_scc0 .LBB0_61
	s_lshl_b64 s[4:5], s[18:19], 22
	v_readlane_b32 s18, v252, 10
	s_add_u32 s4, s18, s4
	v_readlane_b32 s18, v252, 11
	s_addc_u32 s5, s18, s5
	v_lshl_add_u64 v[144:145], v[140:141], 2, s[4:5]
	v_lshlrev_b64 v[150:151], 13, v[142:143]
	s_brev_b32 s4, 63
	v_lshl_add_u64 v[144:145], v[144:145], 0, v[150:151]
	s_mov_b32 s5, -1
	v_lshl_add_u64 v[150:151], v[144:145], 0, s[4:5]
	s_brev_b32 s4, 63
	v_add_co_u32_e32 v152, vcc, s4, v144
	s_mov_b32 s4, 0xfc020000
	s_nop 0
	v_addc_co_u32_e32 v153, vcc, -1, v145, vcc
	s_mov_b32 s5, -1
	global_store_dwordx4 v[152:153], v[128:131], off
	global_store_dwordx4 v[150:151], v[124:127], off offset:64
	global_store_dwordx4 v[150:151], v[120:123], off offset:512
	global_store_dwordx4 v[150:151], v[116:119], off offset:576
	v_lshl_add_u64 v[150:151], v[144:145], 0, s[4:5]
	s_mov_b32 s4, 0xfc020000
	v_add_co_u32_e32 v152, vcc, s4, v144
	s_mov_b32 s4, 0xfc040000
	s_nop 0
	v_addc_co_u32_e32 v153, vcc, -1, v145, vcc
	s_mov_b32 s5, -1
	global_store_dwordx4 v[152:153], v[112:115], off
	global_store_dwordx4 v[150:151], v[108:111], off offset:64
	global_store_dwordx4 v[150:151], v[104:107], off offset:512
	global_store_dwordx4 v[150:151], v[100:103], off offset:576
	v_lshl_add_u64 v[150:151], v[144:145], 0, s[4:5]
	s_mov_b32 s4, 0xfc040000
	v_add_co_u32_e32 v152, vcc, s4, v144
	s_mov_b32 s4, 0xfc060000
	s_nop 0
	v_addc_co_u32_e32 v153, vcc, -1, v145, vcc
	s_mov_b32 s5, -1
	global_store_dwordx4 v[152:153], v[96:99], off
	global_store_dwordx4 v[150:151], v[92:95], off offset:64
	global_store_dwordx4 v[150:151], v[88:91], off offset:512
	global_store_dwordx4 v[150:151], v[84:87], off offset:576
	v_lshl_add_u64 v[150:151], v[144:145], 0, s[4:5]
	s_mov_b32 s4, 0xfc060000
	v_add_co_u32_e32 v152, vcc, s4, v144
	s_mov_b32 s4, 0xfc100000
	s_nop 0
	v_addc_co_u32_e32 v153, vcc, -1, v145, vcc
	s_mov_b32 s5, -1
	global_store_dwordx4 v[152:153], v[80:83], off
	global_store_dwordx4 v[150:151], v[76:79], off offset:64
	global_store_dwordx4 v[150:151], v[72:75], off offset:512
	global_store_dwordx4 v[150:151], v[68:71], off offset:576
	v_lshl_add_u64 v[150:151], v[144:145], 0, s[4:5]
	s_mov_b32 s4, 0xfc100000
	v_add_co_u32_e32 v152, vcc, s4, v144
	s_mov_b32 s4, 0xfc120000
	s_nop 0
	v_addc_co_u32_e32 v153, vcc, -1, v145, vcc
	s_mov_b32 s5, -1
	global_store_dwordx4 v[152:153], v[64:67], off
	global_store_dwordx4 v[150:151], v[60:63], off offset:64
	global_store_dwordx4 v[150:151], v[56:59], off offset:512
	global_store_dwordx4 v[150:151], v[52:55], off offset:576
	v_lshl_add_u64 v[150:151], v[144:145], 0, s[4:5]
	s_mov_b32 s4, 0xfc120000
	v_add_co_u32_e32 v152, vcc, s4, v144
	s_mov_b32 s4, 0xfc140000
	s_nop 0
	v_addc_co_u32_e32 v153, vcc, -1, v145, vcc
	s_mov_b32 s5, -1
	global_store_dwordx4 v[152:153], v[48:51], off
	global_store_dwordx4 v[150:151], v[44:47], off offset:64
	global_store_dwordx4 v[150:151], v[40:43], off offset:512
	global_store_dwordx4 v[150:151], v[36:39], off offset:576
	v_lshl_add_u64 v[150:151], v[144:145], 0, s[4:5]
	s_mov_b32 s4, 0xfc140000
	v_add_co_u32_e32 v152, vcc, s4, v144
	s_mov_b32 s4, 0xfc160000
	s_nop 0
	v_addc_co_u32_e32 v153, vcc, -1, v145, vcc
	s_mov_b32 s5, -1
	global_store_dwordx4 v[152:153], v[32:35], off
	global_store_dwordx4 v[150:151], v[28:31], off offset:64
	global_store_dwordx4 v[150:151], v[24:27], off offset:512
	global_store_dwordx4 v[150:151], v[20:23], off offset:576
	v_lshl_add_u64 v[150:151], v[144:145], 0, s[4:5]
	v_add_co_u32_e32 v144, vcc, 0xfc160000, v144
	s_mov_b64 s[4:5], 0
	s_nop 0
	v_addc_co_u32_e32 v145, vcc, -1, v145, vcc
	global_store_dwordx4 v[144:145], v[16:19], off
	global_store_dwordx4 v[150:151], v[12:15], off offset:64
	global_store_dwordx4 v[150:151], v[8:11], off offset:512
	global_store_dwordx4 v[150:151], v[4:7], off offset:576

; #define PG8_STAGE(bufoff, gbase, voff) do { _Pragma("unroll") for (int _i = 0; _i < 2; ++_i) \
;         __builtin_amdgcn_global_load_lds((const unsigned*)((const char*)(gbase) + (voff)[_i]), (LAS unsigned*)(lds + (bufoff) + ldsw + _i * 8192), 16, 0, 0); } while (0)
; #define PG8_LDA(dst, b, h) do { _Pragma("unroll") for (int m = 0; m < 4; ++m) _Pragma("unroll") for (int k = 0; k < 2; ++k) dst[m][k] = *(const LAS bf16x8*)(lds + PG8_SA(b, h) + aoff + m * 2048 + k * 1024); } while (0)
; #define PG8_LDB(dst, b, h) do { _Pragma("unroll") for (int n = 0; n < 2; ++n) _Pragma("unroll") for (int k = 0; k < 2; ++k) dst[n][k] = *(const LAS bf16x8*)(lds + PG8_SB(b, h) + boff + n * 2048 + k * 1024); } while (0)
; #define PG8_MMA(ai, bj, At, Bt) do { __builtin_amdgcn_s_setprio(1); _Pragma("unroll") for (int m = 0; m < 4; ++m) _Pragma("unroll") for (int n = 0; n < 2; ++n) _Pragma("unroll") for (int k = 0; k < 2; ++k) \
;         acc[ai][bj][m][n] = __builtin_amdgcn_mfma_f32_16x16x32_bf16(Bt[n][k], At[m][k], acc[ai][bj][m][n], 0, 0, 0); __builtin_amdgcn_s_setprio(0); } while (0)
; #define PG8_BAR __builtin_amdgcn_s_barrier()
; template <class Epi, class Sched, int LD>
; __device__ __forceinline__ void gemm_phase(LAS unsigned char* lds, const Gemm g, const Sched& S, const Epi& E) {
;     ...
;         for (int t = 0; t < nt; t += 2) {
;             const bool last = (t == nt - 2);
;             const char* a1 = cA + (size_t)(t + 1) * kstep;
;             const char* a2 = last ? nA : cA + (size_t)(t + 2) * kstep; const char* b2 = last ? nB : cB + (size_t)(t + 2) * kstep;
;             const char* a3 = a2 + kstep; const char* b3 = b2 + kstep;
;             PG8_LDB(B0, 0, 0); PG8_SCHED; PG8_LDA(At, 0, 0); PG8_STAGE(PG8_SA(1, 1), a1 + hstep, voffA);
;             PG8_WAIT_L(8); PG8_BAR; PG8_WAIT_L(0); PG8_MMA(0, 0, At, B0); PG8_BAR; PG8_SCHED;
;             PG8_LDB(B1, 0, 1); PG8_STAGE(PG8_SB(0, 0), b2, voffB);
;             PG8_BAR; PG8_WAIT_L(0); PG8_MMA(0, 1, At, B1); PG8_BAR;
;             PG8_LDA(At, 0, 1); PG8_STAGE(PG8_SA(0, 0), a2, voffA);
;             PG8_BAR; PG8_WAIT_L(0); PG8_MMA(1, 0, At, B0); PG8_BAR; PG8_SCHED;
;             PG8_STAGE(PG8_SB(0, 1), b2 + hstep, voffB);
;             PG8_WAIT_V(6); PG8_BAR; PG8_MMA(1, 1, At, B1); PG8_BAR;
;             PG8_LDB(B0, 1, 0); PG8_SCHED; PG8_LDA(At, 1, 0); PG8_STAGE(PG8_SA(0, 1), a2 + hstep, voffA);
.LBB0_501:
	s_add_u32 s4, s54, 0x4000
	s_addc_u32 s5, s55, 0
	s_cmp_eq_u32 s49, 28
	s_cselect_b32 s4, s50, s4
	s_cselect_b32 s5, s51, s5
	s_cselect_b32 s56, s40, s29
	s_cselect_b32 s57, s41, s47
	s_add_u32 s58, s4, 0x8000
	s_addc_u32 s59, s5, 0
	s_add_i32 s69, 0, 0x10000
	s_add_i32 m0, s52, 0xc000
	ds_read_b128 v[180:183], v146
	ds_read_b128 v[184:187], v146 offset:1024
	ds_read_b128 v[188:191], v146 offset:2048
	ds_read_b128 v[192:195], v146 offset:3072
	ds_read_b128 v[196:199], v146 offset:4096
	ds_read_b128 v[200:203], v146 offset:5120
	ds_read_b128 v[204:207], v146 offset:6144
	ds_read_b128 v[208:211], v146 offset:7168
	global_load_lds_dwordx4 v132, s[54:55]
	s_add_i32 m0, s52, 0xe000
	s_nop 0
	global_load_lds_dwordx4 v138, s[54:55]
	s_waitcnt lgkmcnt(8)
	s_barrier
	s_waitcnt lgkmcnt(0)
	s_setprio 0
	v_mfma_f32_16x16x32_bf16 v[128:131], v[148:151], v[180:183], v[128:131]
	v_mfma_f32_16x16x32_bf16 v[124:127], v[156:159], v[180:183], v[124:127]
	v_mfma_f32_16x16x32_bf16 v[120:123], v[148:151], v[188:191], v[120:123]
	v_mfma_f32_16x16x32_bf16 v[116:119], v[156:159], v[188:191], v[116:119]
	v_mfma_f32_16x16x32_bf16 v[104:107], v[148:151], v[196:199], v[104:107]
	v_mfma_f32_16x16x32_bf16 v[100:103], v[156:159], v[196:199], v[100:103]
	v_mfma_f32_16x16x32_bf16 v[88:91], v[148:151], v[204:207], v[88:91]
	v_mfma_f32_16x16x32_bf16 v[84:87], v[156:159], v[204:207], v[84:87]
	v_mfma_f32_16x16x32_bf16 v[128:131], v[152:155], v[184:187], v[128:131]
	v_mfma_f32_16x16x32_bf16 v[124:127], v[176:179], v[184:187], v[124:127]
	v_mfma_f32_16x16x32_bf16 v[120:123], v[152:155], v[192:195], v[120:123]
	v_mfma_f32_16x16x32_bf16 v[116:119], v[176:179], v[192:195], v[116:119]
	v_mfma_f32_16x16x32_bf16 v[104:107], v[152:155], v[200:203], v[104:107]
	v_mfma_f32_16x16x32_bf16 v[100:103], v[176:179], v[200:203], v[100:103]
	s_barrier
	s_setprio 3
	v_mfma_f32_16x16x32_bf16 v[88:91], v[152:155], v[208:211], v[88:91]
	v_mfma_f32_16x16x32_bf16 v[84:87], v[176:179], v[208:211], v[84:87]
	s_setprio 2
	s_add_i32 s72, 0, 0x14000
	s_add_i32 s69, s69, s39
	ds_read_b128 v[212:215], v228 offset:16384
	ds_read_b128 v[216:219], v228 offset:17408
	ds_read_b128 v[220:223], v228 offset:18432
	ds_read_b128 v[224:227], v228 offset:19456
	s_mov_b32 m0, s69
	s_nop 0
	global_load_lds_dwordx4 v132, s[56:57]
	s_add_i32 m0, s69, 0x2000
	s_nop 0
	global_load_lds_dwordx4 v138, s[56:57]
	s_barrier
	s_waitcnt lgkmcnt(0)
	s_setprio 0
	v_mfma_f32_16x16x32_bf16 v[112:115], v[212:215], v[180:183], v[112:115]
	v_mfma_f32_16x16x32_bf16 v[108:111], v[220:223], v[180:183], v[108:111]
	v_mfma_f32_16x16x32_bf16 v[96:99], v[212:215], v[188:191], v[96:99]
	v_mfma_f32_16x16x32_bf16 v[92:95], v[220:223], v[188:191], v[92:95]
	v_mfma_f32_16x16x32_bf16 v[80:83], v[212:215], v[196:199], v[80:83]
	v_mfma_f32_16x16x32_bf16 v[76:79], v[220:223], v[196:199], v[76:79]
	v_mfma_f32_16x16x32_bf16 v[72:75], v[212:215], v[204:207], v[72:75]
	v_mfma_f32_16x16x32_bf16 v[68:71], v[220:223], v[204:207], v[68:71]
	v_mfma_f32_16x16x32_bf16 v[112:115], v[216:219], v[184:187], v[112:115]
	v_mfma_f32_16x16x32_bf16 v[108:111], v[224:227], v[184:187], v[108:111]
	v_mfma_f32_16x16x32_bf16 v[96:99], v[216:219], v[192:195], v[96:99]
	v_mfma_f32_16x16x32_bf16 v[92:95], v[224:227], v[192:195], v[92:95]
	v_mfma_f32_16x16x32_bf16 v[80:83], v[216:219], v[200:203], v[80:83]
	v_mfma_f32_16x16x32_bf16 v[76:79], v[224:227], v[200:203], v[76:79]
	v_mfma_f32_16x16x32_bf16 v[72:75], v[216:219], v[208:211], v[72:75]
	v_mfma_f32_16x16x32_bf16 v[68:71], v[224:227], v[208:211], v[68:71]
	s_barrier
	s_setprio 2
	s_mov_b32 m0, s52
	ds_read_b128 v[180:183], v146 offset:16384
	ds_read_b128 v[184:187], v146 offset:17408
	ds_read_b128 v[188:191], v146 offset:18432
	ds_read_b128 v[192:195], v146 offset:19456
	ds_read_b128 v[196:199], v146 offset:20480
	ds_read_b128 v[200:203], v146 offset:21504
	ds_read_b128 v[204:207], v146 offset:22528
	ds_read_b128 v[208:211], v146 offset:23552
	global_load_lds_dwordx4 v132, s[4:5]
	s_mov_b32 m0, s53
	s_nop 0
	global_load_lds_dwordx4 v138, s[4:5]
	s_waitcnt vmcnt(10)
	s_barrier
	s_waitcnt lgkmcnt(0)
	s_setprio 0
	v_mfma_f32_16x16x32_bf16 v[64:67], v[148:151], v[180:183], v[64:67]
	v_mfma_f32_16x16x32_bf16 v[60:63], v[156:159], v[180:183], v[60:63]
	v_mfma_f32_16x16x32_bf16 v[56:59], v[148:151], v[188:191], v[56:59]
	v_mfma_f32_16x16x32_bf16 v[52:55], v[156:159], v[188:191], v[52:55]
	v_mfma_f32_16x16x32_bf16 v[40:43], v[148:151], v[196:199], v[40:43]
	v_mfma_f32_16x16x32_bf16 v[36:39], v[156:159], v[196:199], v[36:39]
	v_mfma_f32_16x16x32_bf16 v[24:27], v[148:151], v[204:207], v[24:27]
	v_mfma_f32_16x16x32_bf16 v[20:23], v[156:159], v[204:207], v[20:23]
	v_mfma_f32_16x16x32_bf16 v[64:67], v[152:155], v[184:187], v[64:67]
	v_mfma_f32_16x16x32_bf16 v[60:63], v[176:179], v[184:187], v[60:63]
	v_mfma_f32_16x16x32_bf16 v[56:59], v[152:155], v[192:195], v[56:59]
	v_mfma_f32_16x16x32_bf16 v[52:55], v[176:179], v[192:195], v[52:55]
	v_mfma_f32_16x16x32_bf16 v[40:43], v[152:155], v[200:203], v[40:43]
	v_mfma_f32_16x16x32_bf16 v[36:39], v[176:179], v[200:203], v[36:39]
	s_barrier
	s_setprio 3
	v_mfma_f32_16x16x32_bf16 v[24:27], v[152:155], v[208:211], v[24:27]
	v_mfma_f32_16x16x32_bf16 v[20:23], v[176:179], v[208:211], v[20:23]
	s_setprio 2
	ds_read_b128 v[148:151], v228 offset:32768
	ds_read_b128 v[152:155], v228 offset:33792
	ds_read_b128 v[156:159], v228 offset:34816
	ds_read_b128 v[176:179], v228 offset:35840
	s_add_u32 s70, s56, 0x4000
	s_addc_u32 s71, s57, 0
	s_add_i32 s69, s72, s39
	s_mov_b32 m0, s69
	s_nop 0
	global_load_lds_dwordx4 v132, s[70:71]
	s_add_i32 m0, s69, 0x2000
	s_nop 0
	global_load_lds_dwordx4 v138, s[70:71]
	s_waitcnt vmcnt(6)
	s_barrier
; #define PG8_STAGE(bufoff, gbase, voff) do { _Pragma("unroll") for (int _i = 0; _i < 2; ++_i) \
;         __builtin_amdgcn_global_load_lds((const unsigned*)((const char*)(gbase) + (voff)[_i]), (LAS unsigned*)(lds + (bufoff) + ldsw + _i * 8192), 16, 0, 0); } while (0)
; #define PG8_LDA(dst, b, h) do { _Pragma("unroll") for (int m = 0; m < 4; ++m) _Pragma("unroll") for (int k = 0; k < 2; ++k) dst[m][k] = *(const LAS bf16x8*)(lds + PG8_SA(b, h) + aoff + m * 2048 + k * 1024); } while (0)
; #define PG8_LDB(dst, b, h) do { _Pragma("unroll") for (int n = 0; n < 2; ++n) _Pragma("unroll") for (int k = 0; k < 2; ++k) dst[n][k] = *(const LAS bf16x8*)(lds + PG8_SB(b, h) + boff + n * 2048 + k * 1024); } while (0)
; #define PG8_MMA(ai, bj, At, Bt) do { __builtin_amdgcn_s_setprio(1); _Pragma("unroll") for (int m = 0; m < 4; ++m) _Pragma("unroll") for (int n = 0; n < 2; ++n) _Pragma("unroll") for (int k = 0; k < 2; ++k) \
;         acc[ai][bj][m][n] = __builtin_amdgcn_mfma_f32_16x16x32_bf16(Bt[n][k], At[m][k], acc[ai][bj][m][n], 0, 0, 0); __builtin_amdgcn_s_setprio(0); } while (0)
; #define PG8_WAIT_V(n) asm volatile("s_waitcnt vmcnt(" #n ")" ::: "memory")
; #define PG8_WAIT_L(n) asm volatile("s_waitcnt lgkmcnt(" #n ")" ::: "memory")
; #define PG8_BAR __builtin_amdgcn_s_barrier()
; #define PG8_SCHED __builtin_amdgcn_sched_barrier(0)
; template <class Epi, class Sched, int LD>
; __device__ __forceinline__ void gemm_phase(LAS unsigned char* lds, const Gemm g, const Sched& S, const Epi& E) {
;     ...
;             PG8_WAIT_V(6); PG8_BAR; PG8_MMA(1, 1, At, B1); PG8_BAR;
;             PG8_LDB(B0, 1, 0); PG8_SCHED; PG8_LDA(At, 1, 0); PG8_STAGE(PG8_SA(0, 1), a2 + hstep, voffA);
;             PG8_WAIT_L(8); PG8_BAR; PG8_WAIT_L(0); PG8_MMA(0, 0, At, B0); PG8_BAR; PG8_SCHED;
;             PG8_LDB(B1, 1, 1); PG8_STAGE(PG8_SB(1, 0), b3, voffB);
;             PG8_BAR; PG8_WAIT_L(0); PG8_MMA(0, 1, At, B1); PG8_BAR;
;             PG8_LDA(At, 1, 1); PG8_STAGE(PG8_SA(1, 0), a3, voffA);
;             PG8_BAR; PG8_WAIT_L(0); PG8_MMA(1, 0, At, B0); PG8_BAR; PG8_SCHED;
	s_setprio 0
	v_mfma_f32_16x16x32_bf16 v[48:51], v[212:215], v[180:183], v[48:51]
	v_mfma_f32_16x16x32_bf16 v[44:47], v[220:223], v[180:183], v[44:47]
	v_mfma_f32_16x16x32_bf16 v[32:35], v[212:215], v[188:191], v[32:35]
	v_mfma_f32_16x16x32_bf16 v[28:31], v[220:223], v[188:191], v[28:31]
	v_mfma_f32_16x16x32_bf16 v[16:19], v[212:215], v[196:199], v[16:19]
	v_mfma_f32_16x16x32_bf16 v[12:15], v[220:223], v[196:199], v[12:15]
	v_mfma_f32_16x16x32_bf16 v[8:11], v[212:215], v[204:207], v[8:11]
	v_mfma_f32_16x16x32_bf16 v[4:7], v[220:223], v[204:207], v[4:7]
	v_mfma_f32_16x16x32_bf16 v[48:51], v[216:219], v[184:187], v[48:51]
	v_mfma_f32_16x16x32_bf16 v[44:47], v[224:227], v[184:187], v[44:47]
	v_mfma_f32_16x16x32_bf16 v[32:35], v[216:219], v[192:195], v[32:35]
	v_mfma_f32_16x16x32_bf16 v[28:31], v[224:227], v[192:195], v[28:31]
	v_mfma_f32_16x16x32_bf16 v[16:19], v[216:219], v[200:203], v[16:19]
	v_mfma_f32_16x16x32_bf16 v[12:15], v[224:227], v[200:203], v[12:15]
	v_mfma_f32_16x16x32_bf16 v[8:11], v[216:219], v[208:211], v[8:11]
	v_mfma_f32_16x16x32_bf16 v[4:7], v[224:227], v[208:211], v[4:7]
	s_barrier
	s_setprio 2
	s_add_i32 s69, 0, 0x18000
	s_add_u32 s4, s4, 0x4000
	s_addc_u32 s5, s5, 0
	s_mov_b32 m0, s60
	ds_read_b128 v[180:183], v146 offset:32768
	ds_read_b128 v[184:187], v146 offset:33792
	ds_read_b128 v[188:191], v146 offset:34816
	ds_read_b128 v[192:195], v146 offset:35840
	ds_read_b128 v[196:199], v146 offset:36864
	ds_read_b128 v[200:203], v146 offset:37888
	ds_read_b128 v[204:207], v146 offset:38912
	ds_read_b128 v[208:211], v146 offset:39936
	global_load_lds_dwordx4 v132, s[4:5]
	s_mov_b32 m0, s61
	s_nop 0
	global_load_lds_dwordx4 v138, s[4:5]
	s_waitcnt lgkmcnt(8)
	s_barrier
	s_waitcnt lgkmcnt(0)
	s_setprio 0
	v_mfma_f32_16x16x32_bf16 v[128:131], v[148:151], v[180:183], v[128:131]
	v_mfma_f32_16x16x32_bf16 v[124:127], v[156:159], v[180:183], v[124:127]
	v_mfma_f32_16x16x32_bf16 v[120:123], v[148:151], v[188:191], v[120:123]
	v_mfma_f32_16x16x32_bf16 v[116:119], v[156:159], v[188:191], v[116:119]
	v_mfma_f32_16x16x32_bf16 v[104:107], v[148:151], v[196:199], v[104:107]
	v_mfma_f32_16x16x32_bf16 v[100:103], v[156:159], v[196:199], v[100:103]
	v_mfma_f32_16x16x32_bf16 v[88:91], v[148:151], v[204:207], v[88:91]
	v_mfma_f32_16x16x32_bf16 v[84:87], v[156:159], v[204:207], v[84:87]
	v_mfma_f32_16x16x32_bf16 v[128:131], v[152:155], v[184:187], v[128:131]
	v_mfma_f32_16x16x32_bf16 v[124:127], v[176:179], v[184:187], v[124:127]
	v_mfma_f32_16x16x32_bf16 v[120:123], v[152:155], v[192:195], v[120:123]
	v_mfma_f32_16x16x32_bf16 v[116:119], v[176:179], v[192:195], v[116:119]
	v_mfma_f32_16x16x32_bf16 v[104:107], v[152:155], v[200:203], v[104:107]
	v_mfma_f32_16x16x32_bf16 v[100:103], v[176:179], v[200:203], v[100:103]
	s_barrier
	s_setprio 3
	v_mfma_f32_16x16x32_bf16 v[88:91], v[152:155], v[208:211], v[88:91]
	v_mfma_f32_16x16x32_bf16 v[84:87], v[176:179], v[208:211], v[84:87]
	s_setprio 2
	s_add_i32 s70, 0, 0x1c000
	s_add_u32 s4, s56, 0x8000
	s_addc_u32 s5, s57, 0
	s_add_i32 s69, s69, s39
	ds_read_b128 v[212:215], v228 offset:49152
	ds_read_b128 v[216:219], v228 offset:50176
	ds_read_b128 v[220:223], v228 offset:51200
	ds_read_b128 v[224:227], v228 offset:52224
	s_mov_b32 m0, s69
	s_nop 0
	global_load_lds_dwordx4 v132, s[4:5]
	s_add_i32 m0, s69, 0x2000
	s_nop 0
	global_load_lds_dwordx4 v138, s[4:5]
	s_barrier
	s_waitcnt lgkmcnt(0)
	s_setprio 0
	v_mfma_f32_16x16x32_bf16 v[112:115], v[212:215], v[180:183], v[112:115]
	v_mfma_f32_16x16x32_bf16 v[108:111], v[220:223], v[180:183], v[108:111]
	v_mfma_f32_16x16x32_bf16 v[96:99], v[212:215], v[188:191], v[96:99]
	v_mfma_f32_16x16x32_bf16 v[92:95], v[220:223], v[188:191], v[92:95]
	v_mfma_f32_16x16x32_bf16 v[80:83], v[212:215], v[196:199], v[80:83]
	v_mfma_f32_16x16x32_bf16 v[76:79], v[220:223], v[196:199], v[76:79]
	v_mfma_f32_16x16x32_bf16 v[72:75], v[212:215], v[204:207], v[72:75]
	v_mfma_f32_16x16x32_bf16 v[68:71], v[220:223], v[204:207], v[68:71]
	v_mfma_f32_16x16x32_bf16 v[112:115], v[216:219], v[184:187], v[112:115]
	v_mfma_f32_16x16x32_bf16 v[108:111], v[224:227], v[184:187], v[108:111]
	v_mfma_f32_16x16x32_bf16 v[96:99], v[216:219], v[192:195], v[96:99]
	v_mfma_f32_16x16x32_bf16 v[92:95], v[224:227], v[192:195], v[92:95]
	v_mfma_f32_16x16x32_bf16 v[80:83], v[216:219], v[200:203], v[80:83]
	v_mfma_f32_16x16x32_bf16 v[76:79], v[224:227], v[200:203], v[76:79]
	v_mfma_f32_16x16x32_bf16 v[72:75], v[216:219], v[208:211], v[72:75]
	v_mfma_f32_16x16x32_bf16 v[68:71], v[224:227], v[208:211], v[68:71]
	s_barrier
	s_setprio 2
	s_mov_b32 m0, s64
	ds_read_b128 v[180:183], v146 offset:49152
	ds_read_b128 v[184:187], v146 offset:50176
	ds_read_b128 v[188:191], v146 offset:51200
	ds_read_b128 v[192:195], v146 offset:52224
	ds_read_b128 v[196:199], v146 offset:53248
	ds_read_b128 v[200:203], v146 offset:54272
	ds_read_b128 v[204:207], v146 offset:55296
	ds_read_b128 v[208:211], v146 offset:56320
	global_load_lds_dwordx4 v132, s[58:59]
	s_mov_b32 m0, s65
	s_nop 0
	global_load_lds_dwordx4 v138, s[58:59]
	s_waitcnt vmcnt(10)
	s_barrier
; #define PG8_STAGE(bufoff, gbase, voff) do { _Pragma("unroll") for (int _i = 0; _i < 2; ++_i) \
;         __builtin_amdgcn_global_load_lds((const unsigned*)((const char*)(gbase) + (voff)[_i]), (LAS unsigned*)(lds + (bufoff) + ldsw + _i * 8192), 16, 0, 0); } while (0)
; #define PG8_MMA(ai, bj, At, Bt) do { __builtin_amdgcn_s_setprio(1); _Pragma("unroll") for (int m = 0; m < 4; ++m) _Pragma("unroll") for (int n = 0; n < 2; ++n) _Pragma("unroll") for (int k = 0; k < 2; ++k) \
;         acc[ai][bj][m][n] = __builtin_amdgcn_mfma_f32_16x16x32_bf16(Bt[n][k], At[m][k], acc[ai][bj][m][n], 0, 0, 0); __builtin_amdgcn_s_setprio(0); } while (0)
; #define PG8_WAIT_V(n) asm volatile("s_waitcnt vmcnt(" #n ")" ::: "memory")
; #define PG8_WAIT_L(n) asm volatile("s_waitcnt lgkmcnt(" #n ")" ::: "memory")
; #define PG8_BAR __builtin_amdgcn_s_barrier()
; #define PG8_SCHED __builtin_amdgcn_sched_barrier(0)
;     __device__ __forceinline__ void operator()(const f32x4 (&acc)[2][2][4][2], const Unit& u, int wr, int wc, int fr, int fq) const {
;     ...
;         } else if (wc == 0) {
; #pragma unroll
;             for (int ai = 0; ai < 2; ++ai)
; #pragma unroll
;                 for (int m = 0; m < 4; ++m) {
;                     float* rowp = DT + (size_t)(row0 + ai * HALF + m * 16) * 32 + 8 * fq;
;                     *(f32x4*)rowp = acc[ai][0][m][0]; *(f32x4*)(rowp + 4) = acc[ai][0][m][1];
;                 }
; template <class Epi, class Sched, int LD>
; __device__ __forceinline__ void gemm_phase(LAS unsigned char* lds, const Gemm g, const Sched& S, const Epi& E) {
;     ...
;             PG8_BAR; PG8_WAIT_L(0); PG8_MMA(1, 0, At, B0); PG8_BAR; PG8_SCHED;
;             PG8_STAGE(PG8_SB(1, 1), b3 + hstep, voffB);
;             PG8_WAIT_V(6); PG8_BAR; PG8_MMA(1, 1, At, B1); PG8_BAR;
;         }
	s_waitcnt lgkmcnt(0)
	s_setprio 0
	v_mfma_f32_16x16x32_bf16 v[64:67], v[148:151], v[180:183], v[64:67]
	v_mfma_f32_16x16x32_bf16 v[60:63], v[156:159], v[180:183], v[60:63]
	v_mfma_f32_16x16x32_bf16 v[56:59], v[148:151], v[188:191], v[56:59]
	v_mfma_f32_16x16x32_bf16 v[52:55], v[156:159], v[188:191], v[52:55]
	v_mfma_f32_16x16x32_bf16 v[40:43], v[148:151], v[196:199], v[40:43]
	v_mfma_f32_16x16x32_bf16 v[36:39], v[156:159], v[196:199], v[36:39]
	v_mfma_f32_16x16x32_bf16 v[24:27], v[148:151], v[204:207], v[24:27]
	v_mfma_f32_16x16x32_bf16 v[20:23], v[156:159], v[204:207], v[20:23]
	v_mfma_f32_16x16x32_bf16 v[64:67], v[152:155], v[184:187], v[64:67]
	v_mfma_f32_16x16x32_bf16 v[60:63], v[176:179], v[184:187], v[60:63]
	v_mfma_f32_16x16x32_bf16 v[56:59], v[152:155], v[192:195], v[56:59]
	v_mfma_f32_16x16x32_bf16 v[52:55], v[176:179], v[192:195], v[52:55]
	v_mfma_f32_16x16x32_bf16 v[40:43], v[152:155], v[200:203], v[40:43]
	v_mfma_f32_16x16x32_bf16 v[36:39], v[176:179], v[200:203], v[36:39]
	s_barrier
	s_setprio 3
	v_mfma_f32_16x16x32_bf16 v[24:27], v[152:155], v[208:211], v[24:27]
	v_mfma_f32_16x16x32_bf16 v[20:23], v[176:179], v[208:211], v[20:23]
	s_setprio 2
	ds_read_b128 v[148:151], v228
	ds_read_b128 v[152:155], v228 offset:1024
	ds_read_b128 v[156:159], v228 offset:2048
	ds_read_b128 v[176:179], v228 offset:3072
	s_add_u32 s4, s56, 0xc000
	s_addc_u32 s5, s57, 0
	s_add_i32 s56, s70, s39
	s_mov_b32 m0, s56
	s_nop 0
	global_load_lds_dwordx4 v132, s[4:5]
	s_add_i32 m0, s56, 0x2000
	s_nop 0
	global_load_lds_dwordx4 v138, s[4:5]
	s_waitcnt vmcnt(6)
	s_barrier
	s_setprio 0
	v_mfma_f32_16x16x32_bf16 v[48:51], v[212:215], v[180:183], v[48:51]
	v_mfma_f32_16x16x32_bf16 v[44:47], v[220:223], v[180:183], v[44:47]
	v_mfma_f32_16x16x32_bf16 v[32:35], v[212:215], v[188:191], v[32:35]
	v_mfma_f32_16x16x32_bf16 v[28:31], v[220:223], v[188:191], v[28:31]
	v_mfma_f32_16x16x32_bf16 v[16:19], v[212:215], v[196:199], v[16:19]
	v_mfma_f32_16x16x32_bf16 v[12:15], v[220:223], v[196:199], v[12:15]
	v_mfma_f32_16x16x32_bf16 v[8:11], v[212:215], v[204:207], v[8:11]
	v_mfma_f32_16x16x32_bf16 v[4:7], v[220:223], v[204:207], v[4:7]
	v_mfma_f32_16x16x32_bf16 v[48:51], v[216:219], v[184:187], v[48:51]
	v_mfma_f32_16x16x32_bf16 v[44:47], v[224:227], v[184:187], v[44:47]
	v_mfma_f32_16x16x32_bf16 v[32:35], v[216:219], v[192:195], v[32:35]
	v_mfma_f32_16x16x32_bf16 v[28:31], v[224:227], v[192:195], v[28:31]
	v_mfma_f32_16x16x32_bf16 v[16:19], v[216:219], v[200:203], v[16:19]
	v_mfma_f32_16x16x32_bf16 v[12:15], v[224:227], v[200:203], v[12:15]
	v_mfma_f32_16x16x32_bf16 v[8:11], v[216:219], v[208:211], v[8:11]
	v_mfma_f32_16x16x32_bf16 v[4:7], v[224:227], v[208:211], v[4:7]
	s_barrier
	s_setprio 2
	s_add_i32 s49, s49, 2
	s_add_u32 s54, s54, 0x10000
	s_addc_u32 s55, s55, 0
	s_add_u32 s29, s29, 0x10000
	s_addc_u32 s47, s47, 0
	s_cmp_gt_u32 s49, 29
	s_cbranch_scc0 .LBB0_501
	s_setprio 0
	v_lshl_add_u32 v142, s68, 8, v137
	s_cmp_gt_i32 s67, 35
	s_mov_b64 s[4:5], -1
	s_cbranch_scc0 .LBB0_506
	s_andn2_b64 vcc, exec, s[42:43]
	s_cbranch_vccnz .LBB0_505
	v_or_b32_e32 v150, 16, v142
	v_ashrrev_i32_e32 v143, 31, v142
	v_ashrrev_i32_e32 v151, 31, v150
	v_lshlrev_b64 v[148:149], 7, v[142:143]
	v_lshlrev_b64 v[150:151], 7, v[150:151]
	v_lshl_add_u64 v[148:149], v[140:141], 0, v[148:149]
	v_lshl_add_u64 v[150:151], v[140:141], 0, v[150:151]
	global_store_dwordx4 v[148:149], v[128:131], off
	global_store_dwordx4 v[148:149], v[124:127], off offset:16
	global_store_dwordx4 v[150:151], v[120:123], off
	global_store_dwordx4 v[150:151], v[116:119], off offset:16
	v_or_b32_e32 v150, 32, v142
	v_ashrrev_i32_e32 v151, 31, v150
	v_lshlrev_b64 v[150:151], 7, v[150:151]
	v_lshl_add_u64 v[150:151], v[140:141], 0, v[150:151]
	global_store_dwordx4 v[150:151], v[104:107], off
	global_store_dwordx4 v[150:151], v[100:103], off offset:16
	v_or_b32_e32 v150, 48, v142
	v_ashrrev_i32_e32 v151, 31, v150
	v_lshlrev_b64 v[150:151], 7, v[150:151]
	v_lshl_add_u64 v[150:151], v[140:141], 0, v[150:151]
	s_mov_b64 s[4:5], 0x4000
	global_store_dwordx4 v[150:151], v[88:91], off
	global_store_dwordx4 v[150:151], v[84:87], off offset:16
	v_lshl_add_u64 v[150:151], v[148:149], 0, s[4:5]
	s_movk_i32 s4, 0x4000
	v_add_co_u32_e32 v152, vcc, s4, v148
	s_mov_b64 s[4:5], 0x4800
	s_nop 0
	v_addc_co_u32_e32 v153, vcc, 0, v149, vcc
	global_store_dwordx4 v[152:153], v[64:67], off
	global_store_dwordx4 v[150:151], v[60:63], off offset:16
	v_lshl_add_u64 v[150:151], v[148:149], 0, s[4:5]
	global_store_dwordx4 v[152:153], v[56:59], off offset:2048
	global_store_dwordx4 v[150:151], v[52:55], off offset:16
	s_mov_b64 s[4:5], 0x5000
	v_add_co_u32_e32 v152, vcc, 0x5000, v148
	v_lshl_add_u64 v[150:151], v[148:149], 0, s[4:5]
	s_nop 0
	v_addc_co_u32_e32 v153, vcc, 0, v149, vcc
	s_mov_b64 s[4:5], 0x5800
	global_store_dwordx4 v[152:153], v[40:43], off
	global_store_dwordx4 v[150:151], v[36:39], off offset:16
	v_lshl_add_u64 v[148:149], v[148:149], 0, s[4:5]
	global_store_dwordx4 v[152:153], v[24:27], off offset:2048
	global_store_dwordx4 v[148:149], v[20:23], off offset:16

; #define PG8_STAGE(bufoff, gbase, voff) do { _Pragma("unroll") for (int _i = 0; _i < 2; ++_i) \
;         __builtin_amdgcn_global_load_lds((const unsigned*)((const char*)(gbase) + (voff)[_i]), (LAS unsigned*)(lds + (bufoff) + ldsw + _i * 8192), 16, 0, 0); } while (0)
; #define PG8_LDA(dst, b, h) do { _Pragma("unroll") for (int m = 0; m < 4; ++m) _Pragma("unroll") for (int k = 0; k < 2; ++k) dst[m][k] = *(const LAS bf16x8*)(lds + PG8_SA(b, h) + aoff + m * 2048 + k * 1024); } while (0)
; #define PG8_LDB(dst, b, h) do { _Pragma("unroll") for (int n = 0; n < 2; ++n) _Pragma("unroll") for (int k = 0; k < 2; ++k) dst[n][k] = *(const LAS bf16x8*)(lds + PG8_SB(b, h) + boff + n * 2048 + k * 1024); } while (0)
; #define PG8_WAIT_V(n) asm volatile("s_waitcnt vmcnt(" #n ")" ::: "memory")
; #define PG8_WAIT_L(n) asm volatile("s_waitcnt lgkmcnt(" #n ")" ::: "memory")
; #define PG8_BAR __builtin_amdgcn_s_barrier()
; #define PG8_SCHED __builtin_amdgcn_sched_barrier(0)
; template <class Epi, class Sched, int LD>
; __device__ __forceinline__ void gemm_phase(LAS unsigned char* lds, const Gemm g, const Sched& S, const Epi& E) {
;     ...
;         for (int t = 0; t < nt; t += 2) {
;             const bool last = (t == nt - 2);
;             const char* a1 = cA + (size_t)(t + 1) * kstep;
;             const char* a2 = last ? nA : cA + (size_t)(t + 2) * kstep; const char* b2 = last ? nB : cB + (size_t)(t + 2) * kstep;
;             const char* a3 = a2 + kstep; const char* b3 = b2 + kstep;
;             PG8_LDB(B0, 0, 0); PG8_SCHED; PG8_LDA(At, 0, 0); PG8_STAGE(PG8_SA(1, 1), a1 + hstep, voffA);
;             PG8_WAIT_L(8); PG8_BAR; PG8_WAIT_L(0); PG8_MMA(0, 0, At, B0); PG8_BAR; PG8_SCHED;
;             PG8_LDB(B1, 0, 1); PG8_STAGE(PG8_SB(0, 0), b2, voffB);
;             PG8_BAR; PG8_WAIT_L(0); PG8_MMA(0, 1, At, B1); PG8_BAR;
;             PG8_LDA(At, 0, 1); PG8_STAGE(PG8_SA(0, 0), a2, voffA);
;             PG8_BAR; PG8_WAIT_L(0); PG8_MMA(1, 0, At, B0); PG8_BAR; PG8_SCHED;
;             PG8_STAGE(PG8_SB(0, 1), b2 + hstep, voffB);
;             PG8_WAIT_V(6); PG8_BAR; PG8_MMA(1, 1, At, B1); PG8_BAR;
;             PG8_LDB(B0, 1, 0); PG8_SCHED; PG8_LDA(At, 1, 0); PG8_STAGE(PG8_SA(0, 1), a2 + hstep, voffA);
;             PG8_WAIT_L(8); PG8_BAR; PG8_WAIT_L(0); PG8_MMA(0, 0, At, B0); PG8_BAR; PG8_SCHED;
.LBB0_899:
	s_add_u32 s4, s50, 0x4000
	s_addc_u32 s5, s51, 0
	s_cmp_eq_u32 s70, 28
	s_cselect_b32 s4, s48, s4
	s_cselect_b32 s5, s49, s5
	s_cselect_b32 s54, s40, s45
	s_cselect_b32 s55, s41, s47
	s_add_u32 s56, s4, 0x8000
	s_addc_u32 s57, s5, 0
	s_add_i32 s71, 0, 0x10000
	s_add_i32 m0, s29, 0xc000
	ds_read_b128 v[180:183], v144
	ds_read_b128 v[184:187], v144 offset:1024
	ds_read_b128 v[188:191], v144 offset:2048
	ds_read_b128 v[192:195], v144 offset:3072
	ds_read_b128 v[196:199], v144 offset:4096
	ds_read_b128 v[200:203], v144 offset:5120
	ds_read_b128 v[204:207], v144 offset:6144
	ds_read_b128 v[208:211], v144 offset:7168
	global_load_lds_dwordx4 v138, s[50:51]
	s_add_i32 m0, s29, 0xe000
	s_nop 0
	global_load_lds_dwordx4 v140, s[50:51]
	s_waitcnt lgkmcnt(8)
	s_barrier
	s_waitcnt lgkmcnt(0)
	s_setprio 0
	v_mfma_f32_16x16x32_bf16 v[128:131], v[146:149], v[180:183], v[128:131]
	v_mfma_f32_16x16x32_bf16 v[120:123], v[154:157], v[180:183], v[120:123]
	v_mfma_f32_16x16x32_bf16 v[112:115], v[146:149], v[188:191], v[112:115]
	v_mfma_f32_16x16x32_bf16 v[104:107], v[154:157], v[188:191], v[104:107]
	v_mfma_f32_16x16x32_bf16 v[96:99], v[146:149], v[196:199], v[96:99]
	v_mfma_f32_16x16x32_bf16 v[88:91], v[154:157], v[196:199], v[88:91]
	v_mfma_f32_16x16x32_bf16 v[80:83], v[146:149], v[204:207], v[80:83]
	v_mfma_f32_16x16x32_bf16 v[72:75], v[154:157], v[204:207], v[72:75]
	v_mfma_f32_16x16x32_bf16 v[128:131], v[150:153], v[184:187], v[128:131]
	v_mfma_f32_16x16x32_bf16 v[120:123], v[176:179], v[184:187], v[120:123]
	v_mfma_f32_16x16x32_bf16 v[112:115], v[150:153], v[192:195], v[112:115]
	v_mfma_f32_16x16x32_bf16 v[104:107], v[176:179], v[192:195], v[104:107]
	v_mfma_f32_16x16x32_bf16 v[96:99], v[150:153], v[200:203], v[96:99]
	v_mfma_f32_16x16x32_bf16 v[88:91], v[176:179], v[200:203], v[88:91]
	s_barrier
	s_setprio 3
	v_mfma_f32_16x16x32_bf16 v[80:83], v[150:153], v[208:211], v[80:83]
	v_mfma_f32_16x16x32_bf16 v[72:75], v[176:179], v[208:211], v[72:75]
	s_setprio 2
	s_add_i32 s74, 0, 0x14000
	s_add_i32 s71, s71, s28
	s_mov_b32 m0, s71
	ds_read_b128 v[212:215], v228 offset:16384
	ds_read_b128 v[216:219], v228 offset:17408
	ds_read_b128 v[220:223], v228 offset:18432
	ds_read_b128 v[224:227], v228 offset:19456
	global_load_lds_dwordx4 v138, s[54:55]
	s_add_i32 m0, s71, 0x2000
	s_nop 0
	global_load_lds_dwordx4 v140, s[54:55]
	s_barrier
	s_waitcnt lgkmcnt(0)
	s_setprio 0
	v_mfma_f32_16x16x32_bf16 v[124:127], v[212:215], v[180:183], v[124:127]
	v_mfma_f32_16x16x32_bf16 v[116:119], v[220:223], v[180:183], v[116:119]
	v_mfma_f32_16x16x32_bf16 v[108:111], v[212:215], v[188:191], v[108:111]
	v_mfma_f32_16x16x32_bf16 v[100:103], v[220:223], v[188:191], v[100:103]
	v_mfma_f32_16x16x32_bf16 v[92:95], v[212:215], v[196:199], v[92:95]
	v_mfma_f32_16x16x32_bf16 v[84:87], v[220:223], v[196:199], v[84:87]
	v_mfma_f32_16x16x32_bf16 v[76:79], v[212:215], v[204:207], v[76:79]
	v_mfma_f32_16x16x32_bf16 v[68:71], v[220:223], v[204:207], v[68:71]
	v_mfma_f32_16x16x32_bf16 v[124:127], v[216:219], v[184:187], v[124:127]
	v_mfma_f32_16x16x32_bf16 v[116:119], v[224:227], v[184:187], v[116:119]
	v_mfma_f32_16x16x32_bf16 v[108:111], v[216:219], v[192:195], v[108:111]
	v_mfma_f32_16x16x32_bf16 v[100:103], v[224:227], v[192:195], v[100:103]
	v_mfma_f32_16x16x32_bf16 v[92:95], v[216:219], v[200:203], v[92:95]
	v_mfma_f32_16x16x32_bf16 v[84:87], v[224:227], v[200:203], v[84:87]
	v_mfma_f32_16x16x32_bf16 v[76:79], v[216:219], v[208:211], v[76:79]
	v_mfma_f32_16x16x32_bf16 v[68:71], v[224:227], v[208:211], v[68:71]
	s_barrier
	s_setprio 2
	s_mov_b32 m0, s29
	ds_read_b128 v[180:183], v144 offset:16384
	ds_read_b128 v[184:187], v144 offset:17408
	ds_read_b128 v[188:191], v144 offset:18432
	ds_read_b128 v[192:195], v144 offset:19456
	ds_read_b128 v[196:199], v144 offset:20480
	ds_read_b128 v[200:203], v144 offset:21504
	ds_read_b128 v[204:207], v144 offset:22528
	ds_read_b128 v[208:211], v144 offset:23552
	global_load_lds_dwordx4 v138, s[4:5]
	s_mov_b32 m0, s39
	s_nop 0
	global_load_lds_dwordx4 v140, s[4:5]
	s_waitcnt vmcnt(10)
	s_barrier
	s_waitcnt lgkmcnt(0)
	s_setprio 0
	v_mfma_f32_16x16x32_bf16 v[64:67], v[146:149], v[180:183], v[64:67]
	v_mfma_f32_16x16x32_bf16 v[56:59], v[154:157], v[180:183], v[56:59]
	v_mfma_f32_16x16x32_bf16 v[48:51], v[146:149], v[188:191], v[48:51]
	v_mfma_f32_16x16x32_bf16 v[40:43], v[154:157], v[188:191], v[40:43]
	v_mfma_f32_16x16x32_bf16 v[32:35], v[146:149], v[196:199], v[32:35]
	v_mfma_f32_16x16x32_bf16 v[24:27], v[154:157], v[196:199], v[24:27]
	v_mfma_f32_16x16x32_bf16 v[16:19], v[146:149], v[204:207], v[16:19]
	v_mfma_f32_16x16x32_bf16 v[8:11], v[154:157], v[204:207], v[8:11]
	v_mfma_f32_16x16x32_bf16 v[64:67], v[150:153], v[184:187], v[64:67]
	v_mfma_f32_16x16x32_bf16 v[56:59], v[176:179], v[184:187], v[56:59]
	v_mfma_f32_16x16x32_bf16 v[48:51], v[150:153], v[192:195], v[48:51]
	v_mfma_f32_16x16x32_bf16 v[40:43], v[176:179], v[192:195], v[40:43]
	v_mfma_f32_16x16x32_bf16 v[32:35], v[150:153], v[200:203], v[32:35]
	v_mfma_f32_16x16x32_bf16 v[24:27], v[176:179], v[200:203], v[24:27]
	s_barrier
	s_setprio 3
	v_mfma_f32_16x16x32_bf16 v[16:19], v[150:153], v[208:211], v[16:19]
	v_mfma_f32_16x16x32_bf16 v[8:11], v[176:179], v[208:211], v[8:11]
	s_setprio 2
	ds_read_b128 v[146:149], v228 offset:32768
	ds_read_b128 v[150:153], v228 offset:33792
	ds_read_b128 v[154:157], v228 offset:34816
	ds_read_b128 v[176:179], v228 offset:35840
	s_add_u32 s72, s54, 0x4000
	s_addc_u32 s73, s55, 0
	s_add_i32 s71, s74, s28
	s_mov_b32 m0, s71
	s_nop 0
	global_load_lds_dwordx4 v138, s[72:73]
	s_add_i32 m0, s71, 0x2000
	s_nop 0
	global_load_lds_dwordx4 v140, s[72:73]
	s_waitcnt vmcnt(6)
	s_barrier
; #define PG8_STAGE(bufoff, gbase, voff) do { _Pragma("unroll") for (int _i = 0; _i < 2; ++_i) \
;         __builtin_amdgcn_global_load_lds((const unsigned*)((const char*)(gbase) + (voff)[_i]), (LAS unsigned*)(lds + (bufoff) + ldsw + _i * 8192), 16, 0, 0); } while (0)
; #define PG8_LDA(dst, b, h) do { _Pragma("unroll") for (int m = 0; m < 4; ++m) _Pragma("unroll") for (int k = 0; k < 2; ++k) dst[m][k] = *(const LAS bf16x8*)(lds + PG8_SA(b, h) + aoff + m * 2048 + k * 1024); } while (0)
; #define PG8_LDB(dst, b, h) do { _Pragma("unroll") for (int n = 0; n < 2; ++n) _Pragma("unroll") for (int k = 0; k < 2; ++k) dst[n][k] = *(const LAS bf16x8*)(lds + PG8_SB(b, h) + boff + n * 2048 + k * 1024); } while (0)
; #define PG8_MMA(ai, bj, At, Bt) do { __builtin_amdgcn_s_setprio(1); _Pragma("unroll") for (int m = 0; m < 4; ++m) _Pragma("unroll") for (int n = 0; n < 2; ++n) _Pragma("unroll") for (int k = 0; k < 2; ++k) \
;         acc[ai][bj][m][n] = __builtin_amdgcn_mfma_f32_16x16x32_bf16(Bt[n][k], At[m][k], acc[ai][bj][m][n], 0, 0, 0); __builtin_amdgcn_s_setprio(0); } while (0)
; #define PG8_WAIT_V(n) asm volatile("s_waitcnt vmcnt(" #n ")" ::: "memory")
; #define PG8_WAIT_L(n) asm volatile("s_waitcnt lgkmcnt(" #n ")" ::: "memory")
; #define PG8_BAR __builtin_amdgcn_s_barrier()
; #define PG8_SCHED __builtin_amdgcn_sched_barrier(0)
; template <class Epi, class Sched, int LD>
; __device__ __forceinline__ void gemm_phase(LAS unsigned char* lds, const Gemm g, const Sched& S, const Epi& E) {
;     ...
;             PG8_LDB(B0, 1, 0); PG8_SCHED; PG8_LDA(At, 1, 0); PG8_STAGE(PG8_SA(0, 1), a2 + hstep, voffA);
;             PG8_WAIT_L(8); PG8_BAR; PG8_WAIT_L(0); PG8_MMA(0, 0, At, B0); PG8_BAR; PG8_SCHED;
;             PG8_LDB(B1, 1, 1); PG8_STAGE(PG8_SB(1, 0), b3, voffB);
;             PG8_BAR; PG8_WAIT_L(0); PG8_MMA(0, 1, At, B1); PG8_BAR;
;             PG8_LDA(At, 1, 1); PG8_STAGE(PG8_SA(1, 0), a3, voffA);
;             PG8_BAR; PG8_WAIT_L(0); PG8_MMA(1, 0, At, B0); PG8_BAR; PG8_SCHED;
;             PG8_STAGE(PG8_SB(1, 1), b3 + hstep, voffB);
;             PG8_WAIT_V(6); PG8_BAR; PG8_MMA(1, 1, At, B1); PG8_BAR;
	s_setprio 0
	v_mfma_f32_16x16x32_bf16 v[60:63], v[212:215], v[180:183], v[60:63]
	v_mfma_f32_16x16x32_bf16 v[52:55], v[220:223], v[180:183], v[52:55]
	v_mfma_f32_16x16x32_bf16 v[44:47], v[212:215], v[188:191], v[44:47]
	v_mfma_f32_16x16x32_bf16 v[36:39], v[220:223], v[188:191], v[36:39]
	v_mfma_f32_16x16x32_bf16 v[28:31], v[212:215], v[196:199], v[28:31]
	v_mfma_f32_16x16x32_bf16 v[20:23], v[220:223], v[196:199], v[20:23]
	v_mfma_f32_16x16x32_bf16 v[12:15], v[212:215], v[204:207], v[12:15]
	v_mfma_f32_16x16x32_bf16 v[4:7], v[220:223], v[204:207], v[4:7]
	v_mfma_f32_16x16x32_bf16 v[60:63], v[216:219], v[184:187], v[60:63]
	v_mfma_f32_16x16x32_bf16 v[52:55], v[224:227], v[184:187], v[52:55]
	v_mfma_f32_16x16x32_bf16 v[44:47], v[216:219], v[192:195], v[44:47]
	v_mfma_f32_16x16x32_bf16 v[36:39], v[224:227], v[192:195], v[36:39]
	v_mfma_f32_16x16x32_bf16 v[28:31], v[216:219], v[200:203], v[28:31]
	v_mfma_f32_16x16x32_bf16 v[20:23], v[224:227], v[200:203], v[20:23]
	v_mfma_f32_16x16x32_bf16 v[12:15], v[216:219], v[208:211], v[12:15]
	v_mfma_f32_16x16x32_bf16 v[4:7], v[224:227], v[208:211], v[4:7]
	s_barrier
	s_setprio 2
	s_add_i32 s71, 0, 0x18000
	s_add_u32 s4, s4, 0x4000
	s_addc_u32 s5, s5, 0
	s_mov_b32 m0, s52
	ds_read_b128 v[180:183], v144 offset:32768
	ds_read_b128 v[184:187], v144 offset:33792
	ds_read_b128 v[188:191], v144 offset:34816
	ds_read_b128 v[192:195], v144 offset:35840
	ds_read_b128 v[196:199], v144 offset:36864
	ds_read_b128 v[200:203], v144 offset:37888
	ds_read_b128 v[204:207], v144 offset:38912
	ds_read_b128 v[208:211], v144 offset:39936
	global_load_lds_dwordx4 v138, s[4:5]
	s_mov_b32 m0, s53
	s_nop 0
	global_load_lds_dwordx4 v140, s[4:5]
	s_waitcnt lgkmcnt(8)
	s_barrier
	s_waitcnt lgkmcnt(0)
	s_setprio 0
	v_mfma_f32_16x16x32_bf16 v[128:131], v[146:149], v[180:183], v[128:131]
	v_mfma_f32_16x16x32_bf16 v[120:123], v[154:157], v[180:183], v[120:123]
	v_mfma_f32_16x16x32_bf16 v[112:115], v[146:149], v[188:191], v[112:115]
	v_mfma_f32_16x16x32_bf16 v[104:107], v[154:157], v[188:191], v[104:107]
	v_mfma_f32_16x16x32_bf16 v[96:99], v[146:149], v[196:199], v[96:99]
	v_mfma_f32_16x16x32_bf16 v[88:91], v[154:157], v[196:199], v[88:91]
	v_mfma_f32_16x16x32_bf16 v[80:83], v[146:149], v[204:207], v[80:83]
	v_mfma_f32_16x16x32_bf16 v[72:75], v[154:157], v[204:207], v[72:75]
	v_mfma_f32_16x16x32_bf16 v[128:131], v[150:153], v[184:187], v[128:131]
	v_mfma_f32_16x16x32_bf16 v[120:123], v[176:179], v[184:187], v[120:123]
	v_mfma_f32_16x16x32_bf16 v[112:115], v[150:153], v[192:195], v[112:115]
	v_mfma_f32_16x16x32_bf16 v[104:107], v[176:179], v[192:195], v[104:107]
	v_mfma_f32_16x16x32_bf16 v[96:99], v[150:153], v[200:203], v[96:99]
	v_mfma_f32_16x16x32_bf16 v[88:91], v[176:179], v[200:203], v[88:91]
	s_barrier
	s_setprio 3
	v_mfma_f32_16x16x32_bf16 v[80:83], v[150:153], v[208:211], v[80:83]
	v_mfma_f32_16x16x32_bf16 v[72:75], v[176:179], v[208:211], v[72:75]
	s_setprio 2
	s_add_i32 s72, 0, 0x1c000
	s_add_u32 s4, s54, 0x8000
	s_addc_u32 s5, s55, 0
	s_add_i32 s71, s71, s28
	s_mov_b32 m0, s71
	ds_read_b128 v[212:215], v228 offset:49152
	ds_read_b128 v[216:219], v228 offset:50176
	ds_read_b128 v[220:223], v228 offset:51200
	ds_read_b128 v[224:227], v228 offset:52224
	global_load_lds_dwordx4 v138, s[4:5]
	s_add_i32 m0, s71, 0x2000
	s_nop 0
	global_load_lds_dwordx4 v140, s[4:5]
	s_barrier
	s_waitcnt lgkmcnt(0)
	s_setprio 0
	v_mfma_f32_16x16x32_bf16 v[124:127], v[212:215], v[180:183], v[124:127]
	v_mfma_f32_16x16x32_bf16 v[116:119], v[220:223], v[180:183], v[116:119]
	v_mfma_f32_16x16x32_bf16 v[108:111], v[212:215], v[188:191], v[108:111]
	v_mfma_f32_16x16x32_bf16 v[100:103], v[220:223], v[188:191], v[100:103]
	v_mfma_f32_16x16x32_bf16 v[92:95], v[212:215], v[196:199], v[92:95]
	v_mfma_f32_16x16x32_bf16 v[84:87], v[220:223], v[196:199], v[84:87]
	v_mfma_f32_16x16x32_bf16 v[76:79], v[212:215], v[204:207], v[76:79]
	v_mfma_f32_16x16x32_bf16 v[68:71], v[220:223], v[204:207], v[68:71]
	v_mfma_f32_16x16x32_bf16 v[124:127], v[216:219], v[184:187], v[124:127]
	v_mfma_f32_16x16x32_bf16 v[116:119], v[224:227], v[184:187], v[116:119]
	v_mfma_f32_16x16x32_bf16 v[108:111], v[216:219], v[192:195], v[108:111]
	v_mfma_f32_16x16x32_bf16 v[100:103], v[224:227], v[192:195], v[100:103]
	v_mfma_f32_16x16x32_bf16 v[92:95], v[216:219], v[200:203], v[92:95]
	v_mfma_f32_16x16x32_bf16 v[84:87], v[224:227], v[200:203], v[84:87]
	v_mfma_f32_16x16x32_bf16 v[76:79], v[216:219], v[208:211], v[76:79]
	v_mfma_f32_16x16x32_bf16 v[68:71], v[224:227], v[208:211], v[68:71]
	s_barrier
	s_setprio 2
	s_mov_b32 m0, s60
	ds_read_b128 v[180:183], v144 offset:49152
	ds_read_b128 v[184:187], v144 offset:50176
	ds_read_b128 v[188:191], v144 offset:51200
	ds_read_b128 v[192:195], v144 offset:52224
	ds_read_b128 v[196:199], v144 offset:53248
	ds_read_b128 v[200:203], v144 offset:54272
	ds_read_b128 v[204:207], v144 offset:55296
	ds_read_b128 v[208:211], v144 offset:56320
	global_load_lds_dwordx4 v138, s[56:57]
	s_mov_b32 m0, s61
	s_nop 0
	global_load_lds_dwordx4 v140, s[56:57]
	s_waitcnt vmcnt(10)
	s_barrier
	s_waitcnt lgkmcnt(0)
	s_setprio 0
	v_mfma_f32_16x16x32_bf16 v[64:67], v[146:149], v[180:183], v[64:67]
	v_mfma_f32_16x16x32_bf16 v[56:59], v[154:157], v[180:183], v[56:59]
	v_mfma_f32_16x16x32_bf16 v[48:51], v[146:149], v[188:191], v[48:51]
	v_mfma_f32_16x16x32_bf16 v[40:43], v[154:157], v[188:191], v[40:43]
	v_mfma_f32_16x16x32_bf16 v[32:35], v[146:149], v[196:199], v[32:35]
	v_mfma_f32_16x16x32_bf16 v[24:27], v[154:157], v[196:199], v[24:27]
	v_mfma_f32_16x16x32_bf16 v[16:19], v[146:149], v[204:207], v[16:19]
	v_mfma_f32_16x16x32_bf16 v[8:11], v[154:157], v[204:207], v[8:11]
	v_mfma_f32_16x16x32_bf16 v[64:67], v[150:153], v[184:187], v[64:67]
	v_mfma_f32_16x16x32_bf16 v[56:59], v[176:179], v[184:187], v[56:59]
	v_mfma_f32_16x16x32_bf16 v[48:51], v[150:153], v[192:195], v[48:51]
	v_mfma_f32_16x16x32_bf16 v[40:43], v[176:179], v[192:195], v[40:43]
	v_mfma_f32_16x16x32_bf16 v[32:35], v[150:153], v[200:203], v[32:35]
	v_mfma_f32_16x16x32_bf16 v[24:27], v[176:179], v[200:203], v[24:27]
	s_barrier
; __device__ __forceinline__ unsigned cvt_pk_bf16(float lo, float hi) { f32x2 v = {lo, hi}; bf16x2v b = __builtin_convertvector(v, bf16x2v); return __builtin_bit_cast(unsigned, b); }
; __device__ __forceinline__ float silu_f(float x) { return x * __builtin_amdgcn_rcpf(1.f + __expf(-x)); }
; #define PG8_STAGE(bufoff, gbase, voff) do { _Pragma("unroll") for (int _i = 0; _i < 2; ++_i) \
;         __builtin_amdgcn_global_load_lds((const unsigned*)((const char*)(gbase) + (voff)[_i]), (LAS unsigned*)(lds + (bufoff) + ldsw + _i * 8192), 16, 0, 0); } while (0)
; #define PG8_LDA(dst, b, h) do { _Pragma("unroll") for (int m = 0; m < 4; ++m) _Pragma("unroll") for (int k = 0; k < 2; ++k) dst[m][k] = *(const LAS bf16x8*)(lds + PG8_SA(b, h) + aoff + m * 2048 + k * 1024); } while (0)
; #define PG8_WAIT_V(n) asm volatile("s_waitcnt vmcnt(" #n ")" ::: "memory")
; #define PG8_WAIT_L(n) asm volatile("s_waitcnt lgkmcnt(" #n ")" ::: "memory")
; #define PG8_BAR __builtin_amdgcn_s_barrier()
;     __device__ __forceinline__ void operator()(const f32x4 (&acc)[2][2][4][2], const Unit& u, int wr, int wc, int fr, int fq) const {
;         const int row0 = u.pm * BM + wr * 64 + fr, col0 = u.pn * 128 + wc * 32 + 8 * fq;
; #pragma unroll
;         for (int ai = 0; ai < 2; ++ai)
; #pragma unroll
;             for (int m = 0; m < 4; ++m) {
;                 bf16_t* rowp = O + img_off(row0 + ai * HALF + m * 16, col0, D_FF / 64);
;                 const f32x4 g0 = acc[ai][0][m][0], g1 = acc[ai][0][m][1], u0 = acc[ai][1][m][0], u1 = acc[ai][1][m][1];
;                 u32x4 w;
;                 w.x = cvt_pk_bf16(silu_f(g0[0]) * u0[0], silu_f(g0[1]) * u0[1]); w.y = cvt_pk_bf16(silu_f(g0[2]) * u0[2], silu_f(g0[3]) * u0[3]);
;                 w.z = cvt_pk_bf16(silu_f(g1[0]) * u1[0], silu_f(g1[1]) * u1[1]); w.w = cvt_pk_bf16(silu_f(g1[2]) * u1[2], silu_f(g1[3]) * u1[3]);
;                 *(u32x4*)rowp = w;
; template <class Epi, class Sched, int LD>
; __device__ __forceinline__ void gemm_phase(LAS unsigned char* lds, const Gemm g, const Sched& S, const Epi& E) {
;     ...
;             PG8_LDA(At, 1, 1); PG8_STAGE(PG8_SA(1, 0), a3, voffA);
;             PG8_BAR; PG8_WAIT_L(0); PG8_MMA(1, 0, At, B0); PG8_BAR; PG8_SCHED;
;             PG8_STAGE(PG8_SB(1, 1), b3 + hstep, voffB);
;             PG8_WAIT_V(6); PG8_BAR; PG8_MMA(1, 1, At, B1); PG8_BAR;
;         }
	s_setprio 3
	v_mfma_f32_16x16x32_bf16 v[16:19], v[150:153], v[208:211], v[16:19]
	v_mfma_f32_16x16x32_bf16 v[8:11], v[176:179], v[208:211], v[8:11]
	s_setprio 2
	ds_read_b128 v[146:149], v228
	ds_read_b128 v[150:153], v228 offset:1024
	ds_read_b128 v[154:157], v228 offset:2048
	ds_read_b128 v[176:179], v228 offset:3072
	s_add_u32 s4, s54, 0xc000
	s_addc_u32 s5, s55, 0
	s_add_i32 s54, s72, s28
	s_mov_b32 m0, s54
	s_nop 0
	global_load_lds_dwordx4 v138, s[4:5]
	s_add_i32 m0, s54, 0x2000
	s_nop 0
	global_load_lds_dwordx4 v140, s[4:5]
	s_waitcnt vmcnt(6)
	s_barrier
	s_setprio 0
	v_mfma_f32_16x16x32_bf16 v[60:63], v[212:215], v[180:183], v[60:63]
	v_mfma_f32_16x16x32_bf16 v[52:55], v[220:223], v[180:183], v[52:55]
	v_mfma_f32_16x16x32_bf16 v[44:47], v[212:215], v[188:191], v[44:47]
	v_mfma_f32_16x16x32_bf16 v[36:39], v[220:223], v[188:191], v[36:39]
	v_mfma_f32_16x16x32_bf16 v[28:31], v[212:215], v[196:199], v[28:31]
	v_mfma_f32_16x16x32_bf16 v[20:23], v[220:223], v[196:199], v[20:23]
	v_mfma_f32_16x16x32_bf16 v[12:15], v[212:215], v[204:207], v[12:15]
	v_mfma_f32_16x16x32_bf16 v[4:7], v[220:223], v[204:207], v[4:7]
	v_mfma_f32_16x16x32_bf16 v[60:63], v[216:219], v[184:187], v[60:63]
	v_mfma_f32_16x16x32_bf16 v[52:55], v[224:227], v[184:187], v[52:55]
	v_mfma_f32_16x16x32_bf16 v[44:47], v[216:219], v[192:195], v[44:47]
	v_mfma_f32_16x16x32_bf16 v[36:39], v[224:227], v[192:195], v[36:39]
	v_mfma_f32_16x16x32_bf16 v[28:31], v[216:219], v[200:203], v[28:31]
	v_mfma_f32_16x16x32_bf16 v[20:23], v[224:227], v[200:203], v[20:23]
	v_mfma_f32_16x16x32_bf16 v[12:15], v[216:219], v[208:211], v[12:15]
	v_mfma_f32_16x16x32_bf16 v[4:7], v[224:227], v[208:211], v[4:7]
	s_barrier
	s_setprio 2
	s_add_i32 s70, s70, 2
	s_add_u32 s50, s50, 0x10000
	s_addc_u32 s51, s51, 0
	s_add_u32 s45, s45, 0x10000
	s_addc_u32 s47, s47, 0
	s_cmp_gt_u32 s70, 29
	s_cbranch_scc0 .LBB0_899
	s_setprio 0
	v_mul_f32_e32 v148, 0xbfb8aa3b, v128
	v_mul_f32_e32 v149, 0xbfb8aa3b, v129
	v_exp_f32_e32 v148, v148
	v_exp_f32_e32 v149, v149
	s_lshl_b32 s5, s69, 8
	s_add_i32 s5, s5, s58
	v_add_f32_e32 v148, 1.0, v148
	v_add_f32_e32 v149, 1.0, v149
	v_rcp_f32_e32 v148, v148
	v_rcp_f32_e32 v149, v149
	s_lshl_b32 s4, s68, 7
	s_or_b32 s4, s4, s59
	s_ashr_i32 s45, s5, 8
	v_pk_mul_f32 v[128:129], v[128:129], v[148:149]
	s_ashr_i32 s4, s4, 6
	v_pk_mul_f32 v[124:125], v[128:129], v[124:125]
	s_mulk_i32 s45, 0x58
	v_cvt_pk_bf16_f32 v124, v124, v125
	v_mul_f32_e32 v125, 0xbfb8aa3b, v130
	v_exp_f32_e32 v125, v125
	s_add_i32 s50, s45, s4
	s_ashr_i32 s51, s50, 31
	s_lshl_b64 s[50:51], s[50:51], 15
	v_add_f32_e32 v125, 1.0, v125
	v_rcp_f32_e32 v128, v125
	v_mul_f32_e32 v125, 0xbfb8aa3b, v131
	v_exp_f32_e32 v125, v125
	s_add_u32 s45, s16, s50
	s_addc_u32 s47, s17, s51
	s_lshl_b32 s50, s5, 7
	v_add_f32_e32 v125, 1.0, v125
	v_rcp_f32_e32 v129, v125
	s_and_b32 s50, s50, 0x4000
	s_add_u32 s50, s45, s50
	s_addc_u32 s51, s47, 0
	v_pk_mul_f32 v[128:129], v[130:131], v[128:129]
	s_or_b32 s45, s5, 16
	v_pk_mul_f32 v[126:127], v[128:129], v[126:127]
	s_lshr_b32 s45, s45, 3
	v_cvt_pk_bf16_f32 v125, v126, v127
	v_mul_f32_e32 v126, 0xbfb8aa3b, v120
	v_mul_f32_e32 v127, 0xbfb8aa3b, v121
	v_exp_f32_e32 v126, v126
	v_exp_f32_e32 v127, v127
	v_or_b32_e32 v145, s5, v137
	s_and_b32 s45, s45, 10
	v_add_f32_e32 v126, 1.0, v126
	v_add_f32_e32 v127, 1.0, v127
	v_rcp_f32_e32 v126, v126
	v_rcp_f32_e32 v127, v127
	v_lshlrev_b32_e32 v132, 6, v145
	v_lshlrev_b32_e32 v146, 2, v145
	s_or_b32 s45, s45, s64
	v_pk_mul_f32 v[120:121], v[120:121], v[126:127]
	v_and_or_b32 v132, v132, s15, v142
	v_pk_mul_f32 v[116:117], v[120:121], v[116:117]
	v_and_b32_e32 v146, 32, v146
	v_cvt_pk_bf16_f32 v126, v116, v117
	v_mul_f32_e32 v116, 0xbfb8aa3b, v122
	v_mul_f32_e32 v117, 0xbfb8aa3b, v123
	v_exp_f32_e32 v116, v116
	v_exp_f32_e32 v117, v117
	s_lshl_b32 s45, s45, 10
	v_bitop3_b32 v147, v132, s65, v146 bitop3:0xde
	v_add_f32_e32 v116, 1.0, v116
	v_add_f32_e32 v117, 1.0, v117
	v_rcp_f32_e32 v116, v116
	v_rcp_f32_e32 v117, v117
	s_and_b64 vcc, exec, s[42:43]
	s_mov_b32 s68, s44
	s_mov_b32 s69, s46
	v_pk_mul_f32 v[116:117], v[122:123], v[116:117]
	s_mov_b64 s[54:55], s[40:41]
	v_pk_mul_f32 v[116:117], v[116:117], v[118:119]
	v_bitop3_b32 v118, v132, s45, v146 bitop3:0xde
	v_cvt_pk_bf16_f32 v127, v116, v117
	v_mul_f32_e32 v116, 0xbfb8aa3b, v112
	v_mul_f32_e32 v117, 0xbfb8aa3b, v113
	v_exp_f32_e32 v116, v116
	v_exp_f32_e32 v117, v117
	s_or_b32 s45, s5, 32
	s_or_b32 s5, s5, 48
	v_add_f32_e32 v116, 1.0, v116
	v_add_f32_e32 v117, 1.0, v117
	v_rcp_f32_e32 v116, v116
	v_rcp_f32_e32 v117, v117
	s_lshr_b32 s45, s45, 3
	s_lshr_b32 s5, s5, 3
	s_and_b32 s45, s45, 12
	v_pk_mul_f32 v[112:113], v[112:113], v[116:117]
	s_and_b32 s5, s5, 14
	v_pk_mul_f32 v[108:109], v[112:113], v[108:109]
	s_or_b32 s45, s45, s64
	v_cvt_pk_bf16_f32 v108, v108, v109
	v_mul_f32_e32 v109, 0xbfb8aa3b, v114
	v_exp_f32_e32 v109, v109
	s_or_b32 s5, s5, s64
	s_lshl_b32 s45, s45, 10
	s_lshl_b32 s5, s5, 10
	v_add_f32_e32 v109, 1.0, v109
	v_rcp_f32_e32 v112, v109
	v_mul_f32_e32 v109, 0xbfb8aa3b, v115
	v_exp_f32_e32 v109, v109
	global_store_dwordx4 v147, v[124:127], s[50:51]
	v_add_f32_e32 v109, 1.0, v109
	v_rcp_f32_e32 v113, v109
	s_nop 0
	v_pk_mul_f32 v[112:113], v[114:115], v[112:113]
	s_nop 0
	v_pk_mul_f32 v[110:111], v[112:113], v[110:111]
	s_nop 0
	v_cvt_pk_bf16_f32 v109, v110, v111
	v_mul_f32_e32 v110, 0xbfb8aa3b, v104
	v_mul_f32_e32 v111, 0xbfb8aa3b, v105
	v_exp_f32_e32 v110, v110
	v_exp_f32_e32 v111, v111
	v_add_f32_e32 v110, 1.0, v110
	v_add_f32_e32 v111, 1.0, v111
	v_rcp_f32_e32 v110, v110
	v_rcp_f32_e32 v111, v111
	s_nop 0
	v_pk_mul_f32 v[104:105], v[104:105], v[110:111]
	s_nop 0
; __device__ __forceinline__ unsigned cvt_pk_bf16(float lo, float hi) { f32x2 v = {lo, hi}; bf16x2v b = __builtin_convertvector(v, bf16x2v); return __builtin_bit_cast(unsigned, b); }
; __device__ __forceinline__ float silu_f(float x) { return x * __builtin_amdgcn_rcpf(1.f + __expf(-x)); }
;     __device__ __forceinline__ void operator()(const f32x4 (&acc)[2][2][4][2], const Unit& u, int wr, int wc, int fr, int fq) const {
;         const int row0 = u.pm * BM + wr * 64 + fr, col0 = u.pn * 128 + wc * 32 + 8 * fq;
; #pragma unroll
;         for (int ai = 0; ai < 2; ++ai)
; #pragma unroll
;             for (int m = 0; m < 4; ++m) {
;                 bf16_t* rowp = O + img_off(row0 + ai * HALF + m * 16, col0, D_FF / 64);
;                 const f32x4 g0 = acc[ai][0][m][0], g1 = acc[ai][0][m][1], u0 = acc[ai][1][m][0], u1 = acc[ai][1][m][1];
;                 u32x4 w;
;                 w.x = cvt_pk_bf16(silu_f(g0[0]) * u0[0], silu_f(g0[1]) * u0[1]); w.y = cvt_pk_bf16(silu_f(g0[2]) * u0[2], silu_f(g0[3]) * u0[3]);
;                 w.z = cvt_pk_bf16(silu_f(g1[0]) * u1[0], silu_f(g1[1]) * u1[1]); w.w = cvt_pk_bf16(silu_f(g1[2]) * u1[2], silu_f(g1[3]) * u1[3]);
;                 *(u32x4*)rowp = w;
	v_pk_mul_f32 v[100:101], v[104:105], v[100:101]
	s_nop 0
	v_cvt_pk_bf16_f32 v110, v100, v101
	v_mul_f32_e32 v100, 0xbfb8aa3b, v106
	v_mul_f32_e32 v101, 0xbfb8aa3b, v107
	v_exp_f32_e32 v100, v100
	v_exp_f32_e32 v101, v101
	v_add_f32_e32 v100, 1.0, v100
	v_add_f32_e32 v101, 1.0, v101
	v_rcp_f32_e32 v100, v100
	v_rcp_f32_e32 v101, v101
	s_nop 0
	v_pk_mul_f32 v[100:101], v[106:107], v[100:101]
	s_nop 0
	v_pk_mul_f32 v[100:101], v[100:101], v[102:103]
	v_bitop3_b32 v102, v132, s45, v146 bitop3:0xde
	v_cvt_pk_bf16_f32 v111, v100, v101
	v_mul_f32_e32 v100, 0xbfb8aa3b, v96
	v_mul_f32_e32 v101, 0xbfb8aa3b, v97
	v_exp_f32_e32 v100, v100
	v_exp_f32_e32 v101, v101
	global_store_dwordx4 v118, v[108:111], s[50:51]
	v_add_f32_e32 v100, 1.0, v100
	v_add_f32_e32 v101, 1.0, v101
	v_rcp_f32_e32 v100, v100
	v_rcp_f32_e32 v101, v101
	s_nop 0
	v_pk_mul_f32 v[96:97], v[96:97], v[100:101]
	s_nop 0
	v_pk_mul_f32 v[92:93], v[96:97], v[92:93]
	s_nop 0
	v_cvt_pk_bf16_f32 v92, v92, v93
	v_mul_f32_e32 v93, 0xbfb8aa3b, v98
	v_exp_f32_e32 v93, v93
	s_nop 0
	v_add_f32_e32 v93, 1.0, v93
	v_rcp_f32_e32 v96, v93
	v_mul_f32_e32 v93, 0xbfb8aa3b, v99
	v_exp_f32_e32 v93, v93
	s_nop 0
	v_add_f32_e32 v93, 1.0, v93
	v_rcp_f32_e32 v97, v93
	s_nop 0
	v_pk_mul_f32 v[96:97], v[98:99], v[96:97]
	s_nop 0
	v_pk_mul_f32 v[94:95], v[96:97], v[94:95]
	s_nop 0
	v_cvt_pk_bf16_f32 v93, v94, v95
	v_mul_f32_e32 v94, 0xbfb8aa3b, v88
	v_mul_f32_e32 v95, 0xbfb8aa3b, v89
	v_exp_f32_e32 v94, v94
	v_exp_f32_e32 v95, v95
	v_add_f32_e32 v94, 1.0, v94
	v_add_f32_e32 v95, 1.0, v95
	v_rcp_f32_e32 v94, v94
	v_rcp_f32_e32 v95, v95
	s_nop 0
	v_pk_mul_f32 v[88:89], v[88:89], v[94:95]
	s_nop 0
	v_pk_mul_f32 v[84:85], v[88:89], v[84:85]
	s_nop 0
	v_cvt_pk_bf16_f32 v94, v84, v85
	v_mul_f32_e32 v84, 0xbfb8aa3b, v90
	v_mul_f32_e32 v85, 0xbfb8aa3b, v91
	v_exp_f32_e32 v84, v84
	v_exp_f32_e32 v85, v85
	v_add_f32_e32 v84, 1.0, v84
	v_add_f32_e32 v85, 1.0, v85
	v_rcp_f32_e32 v84, v84
	v_rcp_f32_e32 v85, v85
	s_nop 0
	v_pk_mul_f32 v[84:85], v[90:91], v[84:85]
	s_nop 0
	v_pk_mul_f32 v[84:85], v[84:85], v[86:87]
	v_bitop3_b32 v86, v132, s5, v146 bitop3:0xde
	v_cvt_pk_bf16_f32 v95, v84, v85
	v_mul_f32_e32 v84, 0xbfb8aa3b, v80
	v_mul_f32_e32 v85, 0xbfb8aa3b, v81
	v_exp_f32_e32 v84, v84
	v_exp_f32_e32 v85, v85
	global_store_dwordx4 v102, v[92:95], s[50:51]
	v_add_f32_e32 v84, 1.0, v84
	v_add_f32_e32 v85, 1.0, v85
	v_rcp_f32_e32 v84, v84
	v_rcp_f32_e32 v85, v85
	s_nop 0
	v_pk_mul_f32 v[80:81], v[80:81], v[84:85]
	s_nop 0
	v_pk_mul_f32 v[76:77], v[80:81], v[76:77]
	s_nop 0
	v_cvt_pk_bf16_f32 v76, v76, v77
	v_mul_f32_e32 v77, 0xbfb8aa3b, v82
	v_exp_f32_e32 v77, v77
	s_nop 0
	v_add_f32_e32 v77, 1.0, v77
	v_rcp_f32_e32 v80, v77
	v_mul_f32_e32 v77, 0xbfb8aa3b, v83
	v_exp_f32_e32 v77, v77
	s_nop 0
	v_add_f32_e32 v77, 1.0, v77
	v_rcp_f32_e32 v81, v77
	s_nop 0
	v_pk_mul_f32 v[80:81], v[82:83], v[80:81]
	s_nop 0
	v_pk_mul_f32 v[78:79], v[80:81], v[78:79]
	s_nop 0
	v_cvt_pk_bf16_f32 v77, v78, v79
	v_mul_f32_e32 v78, 0xbfb8aa3b, v72
	v_mul_f32_e32 v79, 0xbfb8aa3b, v73
	v_exp_f32_e32 v78, v78
	v_exp_f32_e32 v79, v79
	v_add_f32_e32 v78, 1.0, v78
	v_add_f32_e32 v79, 1.0, v79
	v_rcp_f32_e32 v78, v78
	v_rcp_f32_e32 v79, v79
	s_nop 0
	v_pk_mul_f32 v[72:73], v[72:73], v[78:79]
	s_nop 0
	v_pk_mul_f32 v[68:69], v[72:73], v[68:69]
	v_mul_f32_e32 v73, 0xbfb8aa3b, v65
	v_cvt_pk_bf16_f32 v78, v68, v69
	v_mul_f32_e32 v68, 0xbfb8aa3b, v74
	v_mul_f32_e32 v69, 0xbfb8aa3b, v75
	v_exp_f32_e32 v68, v68
	v_exp_f32_e32 v69, v69
	v_exp_f32_e32 v73, v73
	v_add_f32_e32 v68, 1.0, v68
	v_add_f32_e32 v69, 1.0, v69
	v_rcp_f32_e32 v68, v68
	v_rcp_f32_e32 v69, v69
	v_add_f32_e32 v73, 1.0, v73
	v_rcp_f32_e32 v73, v73
	v_pk_mul_f32 v[68:69], v[74:75], v[68:69]
	s_nop 0
	v_pk_mul_f32 v[68:69], v[68:69], v[70:71]
	v_add_u32_e32 v70, 0x80, v145
	v_lshlrev_b32_e32 v71, 6, v70
	v_lshlrev_b32_e32 v72, 2, v70
	v_and_or_b32 v71, v71, s15, v142
	v_and_b32_e32 v72, 32, v72
	v_bitop3_b32 v132, v71, s65, v72 bitop3:0xde
	v_mul_f32_e32 v72, 0xbfb8aa3b, v64
	v_exp_f32_e32 v72, v72
	v_cvt_pk_bf16_f32 v79, v68, v69
	v_lshrrev_b32_e32 v68, 8, v70
	v_mov_b32_e32 v69, s4
	v_add_f32_e32 v72, 1.0, v72
	v_rcp_f32_e32 v72, v72
	s_movk_i32 s4, 0x58
	v_mad_i32_i24 v68, v68, s4, v69
	v_ashrrev_i32_e32 v69, 31, v68
	v_pk_mul_f32 v[64:65], v[64:65], v[72:73]
	v_lshlrev_b64 v[68:69], 15, v[68:69]
	v_pk_mul_f32 v[60:61], v[64:65], v[60:61]
	v_lshlrev_b32_e32 v70, 7, v70
	v_cvt_pk_bf16_f32 v60, v60, v61
	v_mul_f32_e32 v61, 0xbfb8aa3b, v66
	v_exp_f32_e32 v61, v61
	v_lshl_add_u64 v[68:69], s[16:17], 0, v[68:69]
	v_and_b32_e32 v70, 0x4000, v70
	v_mov_b32_e32 v71, v133
	v_add_f32_e32 v61, 1.0, v61
	v_rcp_f32_e32 v64, v61
	v_mul_f32_e32 v61, 0xbfb8aa3b, v67
	v_exp_f32_e32 v61, v61
	v_lshl_add_u64 v[70:71], v[68:69], 0, v[70:71]
	v_lshl_add_u64 v[70:71], v[70:71], 0, v[132:133]
	s_mov_b64 s[4:5], s[48:49]
	v_add_f32_e32 v61, 1.0, v61
	v_rcp_f32_e32 v65, v61
	global_store_dwordx4 v86, v[76:79], s[50:51]
	v_pk_mul_f32 v[64:65], v[66:67], v[64:65]
	s_nop 0
	v_pk_mul_f32 v[62:63], v[64:65], v[62:63]
	s_nop 0
	v_cvt_pk_bf16_f32 v61, v62, v63
	v_mul_f32_e32 v62, 0xbfb8aa3b, v56
	v_mul_f32_e32 v63, 0xbfb8aa3b, v57
	v_exp_f32_e32 v62, v62
	v_exp_f32_e32 v63, v63
	v_add_f32_e32 v62, 1.0, v62
	v_add_f32_e32 v63, 1.0, v63
	v_rcp_f32_e32 v62, v62
	v_rcp_f32_e32 v63, v63
	s_nop 0
	v_pk_mul_f32 v[56:57], v[56:57], v[62:63]
	s_nop 0
	v_pk_mul_f32 v[52:53], v[56:57], v[52:53]
	s_nop 0
	v_cvt_pk_bf16_f32 v62, v52, v53
	v_mul_f32_e32 v52, 0xbfb8aa3b, v58
	v_mul_f32_e32 v53, 0xbfb8aa3b, v59
	v_exp_f32_e32 v52, v52
	v_exp_f32_e32 v53, v53
	v_add_f32_e32 v52, 1.0, v52
	v_add_f32_e32 v53, 1.0, v53
	v_rcp_f32_e32 v52, v52
; __device__ __forceinline__ unsigned cvt_pk_bf16(float lo, float hi) { f32x2 v = {lo, hi}; bf16x2v b = __builtin_convertvector(v, bf16x2v); return __builtin_bit_cast(unsigned, b); }
; __device__ __forceinline__ float silu_f(float x) { return x * __builtin_amdgcn_rcpf(1.f + __expf(-x)); }
; #define PG8_WAIT_V(n) asm volatile("s_waitcnt vmcnt(" #n ")" ::: "memory")
; #define PG8_BAR __builtin_amdgcn_s_barrier()
;     __device__ __forceinline__ void operator()(const f32x4 (&acc)[2][2][4][2], const Unit& u, int wr, int wc, int fr, int fq) const {
;         const int row0 = u.pm * BM + wr * 64 + fr, col0 = u.pn * 128 + wc * 32 + 8 * fq;
; #pragma unroll
;         for (int ai = 0; ai < 2; ++ai)
; #pragma unroll
;             for (int m = 0; m < 4; ++m) {
;                 bf16_t* rowp = O + img_off(row0 + ai * HALF + m * 16, col0, D_FF / 64);
;                 const f32x4 g0 = acc[ai][0][m][0], g1 = acc[ai][0][m][1], u0 = acc[ai][1][m][0], u1 = acc[ai][1][m][1];
;                 u32x4 w;
;                 w.x = cvt_pk_bf16(silu_f(g0[0]) * u0[0], silu_f(g0[1]) * u0[1]); w.y = cvt_pk_bf16(silu_f(g0[2]) * u0[2], silu_f(g0[3]) * u0[3]);
;                 w.z = cvt_pk_bf16(silu_f(g1[0]) * u1[0], silu_f(g1[1]) * u1[1]); w.w = cvt_pk_bf16(silu_f(g1[2]) * u1[2], silu_f(g1[3]) * u1[3]);
;                 *(u32x4*)rowp = w;
; template <class Epi, class Sched, int LD>
; __device__ __forceinline__ void gemm_phase(LAS unsigned char* lds, const Gemm g, const Sched& S, const Epi& E) {
;     ...
;         if (!has_next) break;
; #pragma unroll
;         for (int a = 0; a < 2; ++a)
; #pragma unroll
;             for (int b = 0; b < 2; ++b)
; #pragma unroll
;                 for (int m = 0; m < 4; ++m)
; #pragma unroll
;                     for (int n = 0; n < 2; ++n) acc[a][b][m][n] = (f32x4){0.f, 0.f, 0.f, 0.f};
;         cur = nxt; cA = nA; cB = nB; ++ui;
;     }
;     PG8_WAIT_V(0);
;     if (wr == 0) PG8_BAR;
	v_rcp_f32_e32 v53, v53
	s_nop 0
	v_pk_mul_f32 v[52:53], v[58:59], v[52:53]
	s_nop 0
	v_pk_mul_f32 v[52:53], v[52:53], v[54:55]
	s_nop 0
	v_cvt_pk_bf16_f32 v63, v52, v53
	v_add_u32_e32 v52, 0x90, v145
	v_lshrrev_b32_e32 v54, 3, v52
	v_lshlrev_b32_e32 v53, 6, v52
	v_and_or_b32 v54, v54, 10, s64
	v_lshlrev_b32_e32 v55, 2, v52
	v_and_or_b32 v53, v53, s15, v142
	v_lshlrev_b32_e32 v54, 10, v54
	v_and_b32_e32 v55, 32, v55
	v_bitop3_b32 v132, v53, v54, v55 bitop3:0xde
	v_mul_f32_e32 v54, 0xbfb8aa3b, v48
	v_mul_f32_e32 v55, 0xbfb8aa3b, v49
	v_exp_f32_e32 v54, v54
	v_exp_f32_e32 v55, v55
	v_lshlrev_b32_e32 v52, 7, v52
	v_and_b32_e32 v52, 0x4000, v52
	v_add_f32_e32 v54, 1.0, v54
	v_add_f32_e32 v55, 1.0, v55
	v_rcp_f32_e32 v54, v54
	v_rcp_f32_e32 v55, v55
	v_mov_b32_e32 v53, v133
	v_lshl_add_u64 v[52:53], v[68:69], 0, v[52:53]
	v_lshl_add_u64 v[52:53], v[52:53], 0, v[132:133]
	v_pk_mul_f32 v[48:49], v[48:49], v[54:55]
	global_store_dwordx4 v[70:71], v[60:63], off
	v_pk_mul_f32 v[44:45], v[48:49], v[44:45]
	s_nop 0
	v_cvt_pk_bf16_f32 v44, v44, v45
	v_mul_f32_e32 v45, 0xbfb8aa3b, v50
	v_exp_f32_e32 v45, v45
	s_nop 0
	v_add_f32_e32 v45, 1.0, v45
	v_rcp_f32_e32 v48, v45
	v_mul_f32_e32 v45, 0xbfb8aa3b, v51
	v_exp_f32_e32 v45, v45
	s_nop 0
	v_add_f32_e32 v45, 1.0, v45
	v_rcp_f32_e32 v49, v45
	s_nop 0
	v_pk_mul_f32 v[48:49], v[50:51], v[48:49]
	s_nop 0
	v_pk_mul_f32 v[46:47], v[48:49], v[46:47]
	s_nop 0
	v_cvt_pk_bf16_f32 v45, v46, v47
	v_mul_f32_e32 v46, 0xbfb8aa3b, v40
	v_mul_f32_e32 v47, 0xbfb8aa3b, v41
	v_exp_f32_e32 v46, v46
	v_exp_f32_e32 v47, v47
	v_add_f32_e32 v46, 1.0, v46
	v_add_f32_e32 v47, 1.0, v47
	v_rcp_f32_e32 v46, v46
	v_rcp_f32_e32 v47, v47
	s_nop 0
	v_pk_mul_f32 v[40:41], v[40:41], v[46:47]
	s_nop 0
	v_pk_mul_f32 v[36:37], v[40:41], v[36:37]
	s_nop 0
	v_cvt_pk_bf16_f32 v46, v36, v37
	v_mul_f32_e32 v36, 0xbfb8aa3b, v42
	v_mul_f32_e32 v37, 0xbfb8aa3b, v43
	v_exp_f32_e32 v36, v36
	v_exp_f32_e32 v37, v37
	v_add_f32_e32 v36, 1.0, v36
	v_add_f32_e32 v37, 1.0, v37
	v_rcp_f32_e32 v36, v36
	v_rcp_f32_e32 v37, v37
	s_nop 0
	v_pk_mul_f32 v[36:37], v[42:43], v[36:37]
	s_nop 0
	v_pk_mul_f32 v[36:37], v[36:37], v[38:39]
	s_nop 0
	v_cvt_pk_bf16_f32 v47, v36, v37
	v_add_u32_e32 v36, 0xa0, v145
	v_lshrrev_b32_e32 v38, 3, v36
	v_lshlrev_b32_e32 v37, 6, v36
	v_and_or_b32 v38, v38, 12, s64
	v_lshlrev_b32_e32 v39, 2, v36
	v_and_or_b32 v37, v37, s15, v142
	v_lshlrev_b32_e32 v38, 10, v38
	v_and_b32_e32 v39, 32, v39
	v_bitop3_b32 v132, v37, v38, v39 bitop3:0xde
	v_mul_f32_e32 v38, 0xbfb8aa3b, v32
	v_mul_f32_e32 v39, 0xbfb8aa3b, v33
	v_exp_f32_e32 v38, v38
	v_exp_f32_e32 v39, v39
	v_lshlrev_b32_e32 v36, 7, v36
	v_and_b32_e32 v36, 0x4000, v36
	v_add_f32_e32 v38, 1.0, v38
	v_add_f32_e32 v39, 1.0, v39
	v_rcp_f32_e32 v38, v38
	v_rcp_f32_e32 v39, v39
	v_mov_b32_e32 v37, v133
	v_lshl_add_u64 v[36:37], v[68:69], 0, v[36:37]
	v_lshl_add_u64 v[36:37], v[36:37], 0, v[132:133]
	v_pk_mul_f32 v[32:33], v[32:33], v[38:39]
	global_store_dwordx4 v[52:53], v[44:47], off
	v_pk_mul_f32 v[28:29], v[32:33], v[28:29]
	s_nop 0
	v_cvt_pk_bf16_f32 v28, v28, v29
	v_mul_f32_e32 v29, 0xbfb8aa3b, v34
	v_exp_f32_e32 v29, v29
	s_nop 0
	v_add_f32_e32 v29, 1.0, v29
	v_rcp_f32_e32 v32, v29
	v_mul_f32_e32 v29, 0xbfb8aa3b, v35
	v_exp_f32_e32 v29, v29
	s_nop 0
	v_add_f32_e32 v29, 1.0, v29
	v_rcp_f32_e32 v33, v29
	s_nop 0
	v_pk_mul_f32 v[32:33], v[34:35], v[32:33]
	s_nop 0
	v_pk_mul_f32 v[30:31], v[32:33], v[30:31]
	s_nop 0
	v_cvt_pk_bf16_f32 v29, v30, v31
	v_mul_f32_e32 v30, 0xbfb8aa3b, v24
	v_mul_f32_e32 v31, 0xbfb8aa3b, v25
	v_exp_f32_e32 v30, v30
	v_exp_f32_e32 v31, v31
	v_add_f32_e32 v30, 1.0, v30
	v_add_f32_e32 v31, 1.0, v31
	v_rcp_f32_e32 v30, v30
	v_rcp_f32_e32 v31, v31
	s_nop 0
	v_pk_mul_f32 v[24:25], v[24:25], v[30:31]
	s_nop 0
	v_pk_mul_f32 v[20:21], v[24:25], v[20:21]
	s_nop 0
	v_cvt_pk_bf16_f32 v30, v20, v21
	v_mul_f32_e32 v20, 0xbfb8aa3b, v26
	v_mul_f32_e32 v21, 0xbfb8aa3b, v27
	v_exp_f32_e32 v20, v20
	v_exp_f32_e32 v21, v21
	v_add_f32_e32 v20, 1.0, v20
	v_add_f32_e32 v21, 1.0, v21
	v_rcp_f32_e32 v20, v20
	v_rcp_f32_e32 v21, v21
	s_nop 0
	v_pk_mul_f32 v[20:21], v[26:27], v[20:21]
	s_nop 0
	v_pk_mul_f32 v[20:21], v[20:21], v[22:23]
	s_nop 0
	v_cvt_pk_bf16_f32 v31, v20, v21
	v_add_u32_e32 v20, 0xb0, v145
	v_lshrrev_b32_e32 v22, 3, v20
	v_lshlrev_b32_e32 v21, 6, v20
	v_and_or_b32 v22, v22, 14, s64
	v_lshlrev_b32_e32 v23, 2, v20
	v_and_or_b32 v21, v21, s15, v142
	v_lshlrev_b32_e32 v22, 10, v22
	v_and_b32_e32 v23, 32, v23
	v_bitop3_b32 v132, v21, v22, v23 bitop3:0xde
	v_mul_f32_e32 v22, 0xbfb8aa3b, v16
	v_mul_f32_e32 v23, 0xbfb8aa3b, v17
	v_exp_f32_e32 v22, v22
	v_exp_f32_e32 v23, v23
	v_lshlrev_b32_e32 v20, 7, v20
	v_and_b32_e32 v20, 0x4000, v20
	v_add_f32_e32 v22, 1.0, v22
	v_add_f32_e32 v23, 1.0, v23
	v_rcp_f32_e32 v22, v22
	v_rcp_f32_e32 v23, v23
	v_mov_b32_e32 v21, v133
	v_lshl_add_u64 v[20:21], v[68:69], 0, v[20:21]
	v_lshl_add_u64 v[20:21], v[20:21], 0, v[132:133]
	v_pk_mul_f32 v[16:17], v[16:17], v[22:23]
	global_store_dwordx4 v[36:37], v[28:31], off
	v_pk_mul_f32 v[12:13], v[16:17], v[12:13]
	s_nop 0
	v_cvt_pk_bf16_f32 v12, v12, v13
	v_mul_f32_e32 v13, 0xbfb8aa3b, v18
	v_exp_f32_e32 v13, v13
	s_nop 0
	v_add_f32_e32 v13, 1.0, v13
	v_rcp_f32_e32 v16, v13
	v_mul_f32_e32 v13, 0xbfb8aa3b, v19
	v_exp_f32_e32 v13, v13
	s_nop 0
	v_add_f32_e32 v13, 1.0, v13
	v_rcp_f32_e32 v17, v13
	s_nop 0
	v_pk_mul_f32 v[16:17], v[18:19], v[16:17]
	s_nop 0
	v_pk_mul_f32 v[14:15], v[16:17], v[14:15]
	s_nop 0
	v_cvt_pk_bf16_f32 v13, v14, v15
	v_mul_f32_e32 v14, 0xbfb8aa3b, v8
	v_mul_f32_e32 v15, 0xbfb8aa3b, v9
	v_exp_f32_e32 v14, v14
	v_exp_f32_e32 v15, v15
	v_add_f32_e32 v14, 1.0, v14
	v_add_f32_e32 v15, 1.0, v15
	v_rcp_f32_e32 v14, v14
	v_rcp_f32_e32 v15, v15
	s_nop 0
	v_pk_mul_f32 v[8:9], v[8:9], v[14:15]
	s_nop 0
	v_pk_mul_f32 v[4:5], v[8:9], v[4:5]
	s_nop 0
	v_cvt_pk_bf16_f32 v14, v4, v5
	v_mul_f32_e32 v4, 0xbfb8aa3b, v10
	v_mul_f32_e32 v5, 0xbfb8aa3b, v11
	v_exp_f32_e32 v4, v4
	v_exp_f32_e32 v5, v5
	v_add_f32_e32 v4, 1.0, v4
	v_add_f32_e32 v5, 1.0, v5
	v_rcp_f32_e32 v4, v4
	v_rcp_f32_e32 v5, v5
	s_nop 0
	v_pk_mul_f32 v[4:5], v[10:11], v[4:5]
	s_nop 0
	v_pk_mul_f32 v[4:5], v[4:5], v[6:7]
	s_nop 0
	v_cvt_pk_bf16_f32 v15, v4, v5
	global_store_dwordx4 v[20:21], v[12:15], off
	s_cbranch_vccz .LBB0_892
	s_waitcnt vmcnt(0)
	s_cmpk_gt_u32 s2, 0xff
	s_cbranch_scc1 .LBB0_903
	s_barrier
